# v18 + LayerNorm partial statistics of the EpiResid epilogues (phases 2, 6, 10) gathered in LDS and stored as 32 contiguous bytes per row
# speedup vs baseline: 1.0069x; 1.0069x over previous
; #define GASP __attribute__((address_space(1)))
;     __device__ __forceinline__ void operator()(Acc& acc, const Unit& u, int wr, int wc, int fr, int fq, LAS unsigned char* lds) const {
;     ...
;                 const int rl = ai * HALF + wr * 64 + m * 16 + fr, row = u.pm * BM + rl;
;                 const float* rp = (row < split) ? res0 + (size_t)row * D : res1 + (size_t)(row - split) * D;
;                 float* op = out + (size_t)row * D;
;                 f32x2 st = (f32x2){0.f, 1.f}; if (STp) st = SL[rl];
;                 float s = 0.f, q = 0.f;
; #pragma unroll
;                 for (int bj = 0; bj < 2; ++bj)
; #pragma unroll
;                     for (int n = 0; n < 2; ++n) { const int c = col0 + bj * HALF + n * 16; f32x4 r;
;                         if (resb) { const u32x2 w = *(const GASP u32x2*)(resb + (size_t)row * D + c);
;                             r = (f32x4){__uint_as_float(w.x << 16), __uint_as_float(w.x & 0xffff0000u), __uint_as_float(w.y << 16), __uint_as_float(w.y & 0xffff0000u)}; }
;                         else r = *(const GASP f32x4*)(rp + c);
;                         if (STp) r = (r - st[0]) * st[1] * gg[bj][n] + bb[bj][n];
;                         const f32x4 o = r * ALPHA + acc[ai][bj][m][n] * scale;
;                         if (out) *(GASP f32x4*)(op + c) = o;
;                         if (ob) { u32x2 w; w.x = pk2(o[0], o[1]); w.y = pk2(o[2], o[3]); *(GASP u32x2*)(ob + (size_t)row * D + c) = w; }
;                         s += (o[0] + o[1]) + (o[2] + o[3]); q += (o[0] * o[0] + o[1] * o[1]) + (o[2] * o[2] + o[3] * o[3]); }
;                 if (STn) { s += __shfl_xor(s, 16); s += __shfl_xor(s, 32); q += __shfl_xor(q, 16); q += __shfl_xor(q, 32);
;                     if (fq == 0) *(GASP f32x2*)(STn + (size_t)row * 32 + (u.pn * 4 + wc) * 2) = (f32x2){s, q}; }
.LBB0_271:
	v_mbcnt_lo_u32_b32 v238, -1, 0
	v_mbcnt_hi_u32_b32 v238, -1, v238
	v_bfe_u32 v238, v238, 4, 1
	v_mul_u32_u24_e32 v238, 24, v238
	v_mov_b32_e32 v239, 0
	s_lshl_b32 s28, s49, 8
	v_add_u32_e32 v144, s28, v146
	v_ashrrev_i32_e32 v133, 31, v144
	v_cmp_gt_i32_e32 vcc, s41, v144
	v_lshl_or_b32 v142, s48, 8, v148
	v_ashrrev_i32_e32 v143, 31, v142
	v_cndmask_b32_e32 v145, 0, v133, vcc
	v_lshlrev_b64 v[156:157], 11, v[144:145]
	v_lshl_add_u64 v[156:157], s[42:43], 0, v[156:157]
	v_lshl_add_u64 v[158:159], v[142:143], 1, v[156:157]
	global_load_dwordx2 v[160:161], v[158:159], off
	global_load_dwordx2 v[162:163], v[158:159], off offset:32
	global_load_dwordx2 v[164:165], v[158:159], off offset:256
	global_load_dwordx2 v[166:167], v[158:159], off offset:288
	v_and_b32_e32 v156, 64, v155
	v_xor_b32_e32 v133, 16, v155
	v_add_u32_e32 v157, 64, v156
	v_cmp_lt_i32_e32 vcc, v133, v157
	s_lshl_b32 s24, s48, 3
	s_or_b32 s24, s24, s38
	v_cndmask_b32_e32 v133, v155, v133, vcc
	v_lshlrev_b32_e32 v156, 2, v133
	s_ashr_i32 s25, s24, 31
	s_waitcnt vmcnt(0)
	v_lshlrev_b32_e32 v168, 16, v160
	v_and_b32_e32 v169, 0xffff0000, v160
	v_lshlrev_b32_e32 v160, 16, v161
	v_and_b32_e32 v161, 0xffff0000, v161
	v_lshlrev_b32_e32 v170, 16, v162
	v_and_b32_e32 v171, 0xffff0000, v162
	v_lshlrev_b32_e32 v162, 16, v163
	v_and_b32_e32 v163, 0xffff0000, v163
	v_lshlrev_b32_e32 v172, 16, v164
	v_and_b32_e32 v173, 0xffff0000, v164
	v_lshlrev_b32_e32 v164, 16, v165
	v_and_b32_e32 v165, 0xffff0000, v165
	v_lshlrev_b32_e32 v174, 16, v166
	v_and_b32_e32 v175, 0xffff0000, v166
	v_pk_mul_f32 v[168:169], v[168:169], s[20:21] op_sel_hi:[1,0]
	v_pk_mul_f32 v[160:161], v[160:161], s[20:21] op_sel_hi:[1,0]
	v_pk_mul_f32 v[162:163], v[162:163], s[20:21] op_sel_hi:[1,0]
	v_pk_mul_f32 v[164:165], v[164:165], s[20:21] op_sel_hi:[1,0]
	v_lshlrev_b32_e32 v166, 16, v167
	v_and_b32_e32 v167, 0xffff0000, v167
	v_pk_mul_f32 v[170:171], v[170:171], s[20:21] op_sel_hi:[1,0]
	v_pk_mul_f32 v[172:173], v[172:173], s[20:21] op_sel_hi:[1,0]
	v_pk_mul_f32 v[174:175], v[174:175], s[20:21] op_sel_hi:[1,0]
	v_pk_fma_f32 v[126:127], v[126:127], 0.5, v[160:161] op_sel_hi:[1,0,1]
	v_pk_fma_f32 v[124:125], v[124:125], 0.5, v[168:169] op_sel_hi:[1,0,1]
	v_pk_fma_f32 v[122:123], v[122:123], 0.5, v[162:163] op_sel_hi:[1,0,1]
	v_pk_fma_f32 v[118:119], v[118:119], 0.5, v[164:165] op_sel_hi:[1,0,1]
	v_pk_mul_f32 v[166:167], v[166:167], s[20:21] op_sel_hi:[1,0]
	v_pk_fma_f32 v[120:121], v[120:121], 0.5, v[170:171] op_sel_hi:[1,0,1]
	v_pk_fma_f32 v[116:117], v[116:117], 0.5, v[172:173] op_sel_hi:[1,0,1]
	v_pk_fma_f32 v[162:163], v[112:113], 0.5, v[174:175] op_sel_hi:[1,0,1]
	v_cvt_pk_bf16_f32 v228, v124, v125
	v_cvt_pk_bf16_f32 v229, v126, v127
	v_mul_f32_e32 v172, v122, v122
	v_mul_f32_e32 v173, v118, v118
	v_pk_fma_f32 v[160:161], v[114:115], 0.5, v[166:167] op_sel_hi:[1,0,1]
	v_add_f32_e32 v114, v124, v125
	v_add_f32_e32 v164, v126, v127
	v_mul_f32_e32 v167, v124, v124
	v_mul_f32_e32 v125, v125, v125
	v_mul_f32_e32 v169, v126, v126
	v_mul_f32_e32 v127, v127, v127
	v_cvt_pk_bf16_f32 v230, v120, v121
	v_cvt_pk_bf16_f32 v231, v122, v123
	v_mul_f32_e32 v115, v120, v120
	v_mul_f32_e32 v165, v121, v121
	v_mov_b32_e32 v166, v120
	v_mov_b32_e32 v124, v121
	v_mov_b32_e32 v168, v122
	v_mov_b32_e32 v126, v123
	s_nop 1
	v_permlane16_swap_b32_e32 v228, v230
	v_permlane16_swap_b32_e32 v229, v231
	v_lshl_add_u64 v[236:237], v[158:159], 0, v[238:239]
	global_store_dwordx4 v[236:237], v[228:231], off
	v_pk_fma_f32 v[112:113], v[122:123], v[122:123], v[172:173] op_sel_hi:[1,1,0]
	v_cvt_pk_bf16_f32 v232, v116, v117
	v_mul_f32_e32 v177, v116, v116
	v_mul_f32_e32 v179, v117, v117
	v_mul_f32_e32 v181, v119, v119
	v_mov_b32_e32 v176, v116
	v_mov_b32_e32 v178, v117
	v_pk_add_f32 v[116:117], v[166:167], v[124:125]
	v_pk_add_f32 v[120:121], v[168:169], v[126:127]
	v_pk_add_f32 v[114:115], v[114:115], v[164:165]
	v_mov_b32_e32 v133, v113
	v_mov_b32_e32 v172, v118
	v_mov_b32_e32 v180, v119
	v_pk_add_f32 v[122:123], v[176:177], v[178:179]
	v_pk_add_f32 v[116:117], v[116:117], v[120:121]
	v_pk_add_f32 v[112:113], v[114:115], v[132:133]
	v_pk_add_f32 v[114:115], v[172:173], v[180:181]
	v_mul_f32_e32 v183, v162, v162
	v_mul_f32_e32 v185, v163, v163
	v_mul_f32_e32 v187, v160, v160
	v_mul_f32_e32 v189, v161, v161
	v_pk_add_f32 v[112:113], v[116:117], v[112:113]
	v_pk_add_f32 v[114:115], v[122:123], v[114:115]
	v_mov_b32_e32 v182, v162
	v_mov_b32_e32 v184, v163
	v_mov_b32_e32 v186, v160
	v_mov_b32_e32 v188, v161
	v_pk_add_f32 v[112:113], v[112:113], v[114:115]
	v_pk_add_f32 v[114:115], v[182:183], v[184:185]
	v_pk_add_f32 v[116:117], v[186:187], v[188:189]
	v_cvt_pk_bf16_f32 v233, v118, v119
	v_pk_add_f32 v[114:115], v[114:115], v[116:117]
	v_xor_b32_e32 v116, 32, v155
	v_pk_add_f32 v[112:113], v[112:113], v[114:115]
	ds_bpermute_b32 v114, v156, v112
	ds_bpermute_b32 v115, v156, v113
	v_cmp_lt_i32_e32 vcc, v116, v157
	v_cvt_pk_bf16_f32 v234, v162, v163
	v_cvt_pk_bf16_f32 v235, v160, v161
	v_cndmask_b32_e32 v116, v155, v116, vcc
	v_lshlrev_b32_e32 v116, 2, v116
	s_waitcnt lgkmcnt(0)
	v_pk_add_f32 v[112:113], v[112:113], v[114:115]
	ds_bpermute_b32 v114, v116, v112
	ds_bpermute_b32 v115, v116, v113
	s_nop 1
	v_permlane16_swap_b32_e32 v232, v234
	v_permlane16_swap_b32_e32 v233, v235
	global_store_dwordx4 v[236:237], v[232:235], off offset:256
	s_and_saveexec_b64 s[26:27], s[6:7]
	s_cbranch_execz .LBB0_273
	s_waitcnt lgkmcnt(0)
	v_pk_add_f32 v[112:113], v[112:113], v[114:115]
	v_and_b32_e32 v114, 0xff, v144
	v_bfe_u32 v115, v208, 6, 2
	v_lshlrev_b32_e32 v114, 5, v114
	v_lshl_add_u32 v114, v115, 3, v114
	v_add_u32_e32 v114, 0x20800, v114
	ds_write_b64 v114, v[112:113]
; #define GASP __attribute__((address_space(1)))
;     __device__ __forceinline__ void operator()(Acc& acc, const Unit& u, int wr, int wc, int fr, int fq, LAS unsigned char* lds) const {
;     ...
;                 const int rl = ai * HALF + wr * 64 + m * 16 + fr, row = u.pm * BM + rl;
;                 const float* rp = (row < split) ? res0 + (size_t)row * D : res1 + (size_t)(row - split) * D;
;                 float* op = out + (size_t)row * D;
;                 f32x2 st = (f32x2){0.f, 1.f}; if (STp) st = SL[rl];
;                 float s = 0.f, q = 0.f;
; #pragma unroll
;                 for (int bj = 0; bj < 2; ++bj)
; #pragma unroll
;                     for (int n = 0; n < 2; ++n) { const int c = col0 + bj * HALF + n * 16; f32x4 r;
;                         if (resb) { const u32x2 w = *(const GASP u32x2*)(resb + (size_t)row * D + c);
;                             r = (f32x4){__uint_as_float(w.x << 16), __uint_as_float(w.x & 0xffff0000u), __uint_as_float(w.y << 16), __uint_as_float(w.y & 0xffff0000u)}; }
;                         else r = *(const GASP f32x4*)(rp + c);
;                         if (STp) r = (r - st[0]) * st[1] * gg[bj][n] + bb[bj][n];
;                         const f32x4 o = r * ALPHA + acc[ai][bj][m][n] * scale;
;                         if (out) *(GASP f32x4*)(op + c) = o;
;                         if (ob) { u32x2 w; w.x = pk2(o[0], o[1]); w.y = pk2(o[2], o[3]); *(GASP u32x2*)(ob + (size_t)row * D + c) = w; }
;                         s += (o[0] + o[1]) + (o[2] + o[3]); q += (o[0] * o[0] + o[1] * o[1]) + (o[2] * o[2] + o[3] * o[3]); }
;                 if (STn) { s += __shfl_xor(s, 16); s += __shfl_xor(s, 32); q += __shfl_xor(q, 16); q += __shfl_xor(q, 32);
;                     if (fq == 0) *(GASP f32x2*)(STn + (size_t)row * 32 + (u.pn * 4 + wc) * 2) = (f32x2){s, q}; }
.LBB0_273:
	s_or_b64 exec, exec, s[26:27]
	v_add_u32_e32 v112, s28, v149
	v_ashrrev_i32_e32 v113, 31, v112
	v_cmp_gt_i32_e32 vcc, s41, v112
	s_nop 1
	v_cndmask_b32_e32 v113, 0, v113, vcc
	s_waitcnt lgkmcnt(0)
	v_lshlrev_b64 v[114:115], 11, v[112:113]
	v_lshl_add_u64 v[114:115], s[42:43], 0, v[114:115]
	v_lshl_add_u64 v[114:115], v[142:143], 1, v[114:115]
	global_load_dwordx2 v[118:119], v[114:115], off
	global_load_dwordx2 v[120:121], v[114:115], off offset:32
	global_load_dwordx2 v[122:123], v[114:115], off offset:256
	global_load_dwordx2 v[124:125], v[114:115], off offset:288
	s_waitcnt vmcnt(3)
	v_lshlrev_b32_e32 v126, 16, v118
	s_waitcnt vmcnt(2)
	v_lshlrev_b32_e32 v158, 16, v120
	v_and_b32_e32 v159, 0xffff0000, v120
	v_lshlrev_b32_e32 v120, 16, v121
	v_and_b32_e32 v121, 0xffff0000, v121
	v_and_b32_e32 v127, 0xffff0000, v118
	v_lshlrev_b32_e32 v118, 16, v119
	v_and_b32_e32 v119, 0xffff0000, v119
	s_waitcnt vmcnt(1)
	v_lshlrev_b32_e32 v160, 16, v122
	v_and_b32_e32 v161, 0xffff0000, v122
	v_pk_mul_f32 v[120:121], v[120:121], s[20:21] op_sel_hi:[1,0]
	v_lshlrev_b32_e32 v122, 16, v123
	v_and_b32_e32 v123, 0xffff0000, v123
	s_waitcnt vmcnt(0)
	v_lshlrev_b32_e32 v162, 16, v124
	v_and_b32_e32 v163, 0xffff0000, v124
	v_lshlrev_b32_e32 v124, 16, v125
	v_and_b32_e32 v125, 0xffff0000, v125
	v_pk_mul_f32 v[126:127], v[126:127], s[20:21] op_sel_hi:[1,0]
	v_pk_mul_f32 v[118:119], v[118:119], s[20:21] op_sel_hi:[1,0]
	v_pk_mul_f32 v[158:159], v[158:159], s[20:21] op_sel_hi:[1,0]
	v_pk_mul_f32 v[160:161], v[160:161], s[20:21] op_sel_hi:[1,0]
	v_pk_fma_f32 v[106:107], v[106:107], 0.5, v[120:121] op_sel_hi:[1,0,1]
	v_pk_mul_f32 v[122:123], v[122:123], s[20:21] op_sel_hi:[1,0]
	v_pk_mul_f32 v[162:163], v[162:163], s[20:21] op_sel_hi:[1,0]
	v_pk_mul_f32 v[124:125], v[124:125], s[20:21] op_sel_hi:[1,0]
	v_pk_fma_f32 v[110:111], v[110:111], 0.5, v[118:119] op_sel_hi:[1,0,1]
	v_pk_fma_f32 v[108:109], v[108:109], 0.5, v[126:127] op_sel_hi:[1,0,1]
	v_pk_fma_f32 v[104:105], v[104:105], 0.5, v[158:159] op_sel_hi:[1,0,1]
	v_pk_fma_f32 v[100:101], v[100:101], 0.5, v[160:161] op_sel_hi:[1,0,1]
	v_mul_f32_e32 v160, v106, v106
	v_pk_fma_f32 v[102:103], v[102:103], 0.5, v[122:123] op_sel_hi:[1,0,1]
	v_pk_fma_f32 v[118:119], v[98:99], 0.5, v[124:125] op_sel_hi:[1,0,1]
	v_pk_fma_f32 v[120:121], v[96:97], 0.5, v[162:163] op_sel_hi:[1,0,1]
	v_cvt_pk_bf16_f32 v228, v108, v109
	v_cvt_pk_bf16_f32 v229, v110, v111
	v_add_f32_e32 v98, v108, v109
	v_add_f32_e32 v122, v110, v111
	v_mul_f32_e32 v125, v108, v108
	v_mul_f32_e32 v109, v109, v109
	v_mul_f32_e32 v127, v110, v110
	v_mul_f32_e32 v111, v111, v111
	v_cvt_pk_bf16_f32 v230, v104, v105
	v_mul_f32_e32 v99, v104, v104
	v_mul_f32_e32 v123, v105, v105
	v_mov_b32_e32 v124, v104
	v_mov_b32_e32 v108, v105
	v_mov_b32_e32 v126, v106
	v_mov_b32_e32 v110, v107
	v_pk_fma_f32 v[104:105], v[106:107], v[106:107], v[160:161] op_sel_hi:[1,1,0]
	v_cvt_pk_bf16_f32 v231, v106, v107
	v_mul_f32_e32 v163, v100, v100
	v_mul_f32_e32 v165, v101, v101
	v_mul_f32_e32 v167, v102, v102
	v_mul_f32_e32 v169, v103, v103
	v_mov_b32_e32 v162, v100
	v_mov_b32_e32 v164, v101
	v_mov_b32_e32 v166, v102
	v_mov_b32_e32 v168, v103
	v_pk_add_f32 v[106:107], v[124:125], v[108:109]
	v_pk_add_f32 v[108:109], v[126:127], v[110:111]
	v_pk_add_f32 v[98:99], v[98:99], v[122:123]
	v_mov_b32_e32 v133, v105
	v_mul_f32_e32 v171, v120, v120
	v_mul_f32_e32 v173, v121, v121
	v_mul_f32_e32 v175, v118, v118
	v_mul_f32_e32 v177, v119, v119
	v_mov_b32_e32 v170, v120
	v_mov_b32_e32 v172, v121
	v_mov_b32_e32 v174, v118
	v_mov_b32_e32 v176, v119
	v_pk_add_f32 v[110:111], v[162:163], v[164:165]
	v_pk_add_f32 v[122:123], v[166:167], v[168:169]
	v_pk_add_f32 v[106:107], v[106:107], v[108:109]
	v_pk_add_f32 v[98:99], v[98:99], v[132:133]
	v_pk_add_f32 v[124:125], v[170:171], v[172:173]
	v_pk_add_f32 v[126:127], v[174:175], v[176:177]
	v_pk_add_f32 v[104:105], v[110:111], v[122:123]
	v_pk_add_f32 v[98:99], v[106:107], v[98:99]
	v_pk_add_f32 v[108:109], v[124:125], v[126:127]
	v_pk_add_f32 v[98:99], v[98:99], v[104:105]
	s_nop 1
	v_permlane16_swap_b32_e32 v228, v230
	v_permlane16_swap_b32_e32 v229, v231
	v_lshl_add_u64 v[236:237], v[114:115], 0, v[238:239]
	global_store_dwordx4 v[236:237], v[228:231], off
	v_pk_add_f32 v[98:99], v[98:99], v[108:109]
	ds_bpermute_b32 v104, v156, v98
	ds_bpermute_b32 v105, v156, v99
	v_cvt_pk_bf16_f32 v232, v100, v101
	v_cvt_pk_bf16_f32 v233, v102, v103
	v_cvt_pk_bf16_f32 v234, v120, v121
	s_waitcnt lgkmcnt(0)
	v_pk_add_f32 v[96:97], v[98:99], v[104:105]
	ds_bpermute_b32 v98, v116, v96
	ds_bpermute_b32 v99, v116, v97
	v_cvt_pk_bf16_f32 v235, v118, v119
	s_nop 1
	v_permlane16_swap_b32_e32 v232, v234
	v_permlane16_swap_b32_e32 v233, v235
	global_store_dwordx4 v[236:237], v[232:235], off offset:256
	s_and_saveexec_b64 s[26:27], s[6:7]
	s_cbranch_execz .LBB0_275
	s_waitcnt lgkmcnt(0)
	v_pk_add_f32 v[96:97], v[96:97], v[98:99]
	v_and_b32_e32 v98, 0xff, v112
	v_bfe_u32 v99, v208, 6, 2
	v_lshlrev_b32_e32 v98, 5, v98
	v_lshl_add_u32 v98, v99, 3, v98
	v_add_u32_e32 v98, 0x20800, v98
	ds_write_b64 v98, v[96:97]
; #define GASP __attribute__((address_space(1)))
;     __device__ __forceinline__ void operator()(Acc& acc, const Unit& u, int wr, int wc, int fr, int fq, LAS unsigned char* lds) const {
;     ...
;                 const int rl = ai * HALF + wr * 64 + m * 16 + fr, row = u.pm * BM + rl;
;                 const float* rp = (row < split) ? res0 + (size_t)row * D : res1 + (size_t)(row - split) * D;
;                 float* op = out + (size_t)row * D;
;                 f32x2 st = (f32x2){0.f, 1.f}; if (STp) st = SL[rl];
;                 float s = 0.f, q = 0.f;
; #pragma unroll
;                 for (int bj = 0; bj < 2; ++bj)
; #pragma unroll
;                     for (int n = 0; n < 2; ++n) { const int c = col0 + bj * HALF + n * 16; f32x4 r;
;                         if (resb) { const u32x2 w = *(const GASP u32x2*)(resb + (size_t)row * D + c);
;                             r = (f32x4){__uint_as_float(w.x << 16), __uint_as_float(w.x & 0xffff0000u), __uint_as_float(w.y << 16), __uint_as_float(w.y & 0xffff0000u)}; }
;                         else r = *(const GASP f32x4*)(rp + c);
;                         if (STp) r = (r - st[0]) * st[1] * gg[bj][n] + bb[bj][n];
;                         const f32x4 o = r * ALPHA + acc[ai][bj][m][n] * scale;
;                         if (out) *(GASP f32x4*)(op + c) = o;
;                         if (ob) { u32x2 w; w.x = pk2(o[0], o[1]); w.y = pk2(o[2], o[3]); *(GASP u32x2*)(ob + (size_t)row * D + c) = w; }
;                         s += (o[0] + o[1]) + (o[2] + o[3]); q += (o[0] * o[0] + o[1] * o[1]) + (o[2] * o[2] + o[3] * o[3]); }
;                 if (STn) { s += __shfl_xor(s, 16); s += __shfl_xor(s, 32); q += __shfl_xor(q, 16); q += __shfl_xor(q, 32);
;                     if (fq == 0) *(GASP f32x2*)(STn + (size_t)row * 32 + (u.pn * 4 + wc) * 2) = (f32x2){s, q}; }
.LBB0_275:
	s_or_b64 exec, exec, s[26:27]
	v_add_u32_e32 v96, s28, v150
	v_ashrrev_i32_e32 v97, 31, v96
	v_cmp_gt_i32_e32 vcc, s41, v96
	s_nop 1
	v_cndmask_b32_e32 v97, 0, v97, vcc
	s_waitcnt lgkmcnt(0)
	v_lshlrev_b64 v[98:99], 11, v[96:97]
	v_lshl_add_u64 v[98:99], s[42:43], 0, v[98:99]
	v_lshl_add_u64 v[98:99], v[142:143], 1, v[98:99]
	global_load_dwordx2 v[100:101], v[98:99], off
	global_load_dwordx2 v[102:103], v[98:99], off offset:32
	global_load_dwordx2 v[104:105], v[98:99], off offset:256
	global_load_dwordx2 v[106:107], v[98:99], off offset:288
	s_waitcnt vmcnt(3)
	v_lshlrev_b32_e32 v108, 16, v100
	s_waitcnt vmcnt(2)
	v_lshlrev_b32_e32 v110, 16, v102
	v_and_b32_e32 v111, 0xffff0000, v102
	v_lshlrev_b32_e32 v102, 16, v103
	v_and_b32_e32 v103, 0xffff0000, v103
	v_and_b32_e32 v109, 0xffff0000, v100
	v_lshlrev_b32_e32 v100, 16, v101
	v_and_b32_e32 v101, 0xffff0000, v101
	s_waitcnt vmcnt(1)
	v_lshlrev_b32_e32 v112, 16, v104
	v_and_b32_e32 v113, 0xffff0000, v104
	v_pk_mul_f32 v[102:103], v[102:103], s[20:21] op_sel_hi:[1,0]
	v_lshlrev_b32_e32 v104, 16, v105
	v_and_b32_e32 v105, 0xffff0000, v105
	s_waitcnt vmcnt(0)
	v_lshlrev_b32_e32 v114, 16, v106
	v_and_b32_e32 v115, 0xffff0000, v106
	v_lshlrev_b32_e32 v106, 16, v107
	v_and_b32_e32 v107, 0xffff0000, v107
	v_pk_mul_f32 v[108:109], v[108:109], s[20:21] op_sel_hi:[1,0]
	v_pk_mul_f32 v[100:101], v[100:101], s[20:21] op_sel_hi:[1,0]
	v_pk_mul_f32 v[110:111], v[110:111], s[20:21] op_sel_hi:[1,0]
	v_pk_mul_f32 v[112:113], v[112:113], s[20:21] op_sel_hi:[1,0]
	v_pk_fma_f32 v[90:91], v[90:91], 0.5, v[102:103] op_sel_hi:[1,0,1]
	v_pk_mul_f32 v[104:105], v[104:105], s[20:21] op_sel_hi:[1,0]
	v_pk_mul_f32 v[114:115], v[114:115], s[20:21] op_sel_hi:[1,0]
	v_pk_mul_f32 v[106:107], v[106:107], s[20:21] op_sel_hi:[1,0]
	v_pk_fma_f32 v[94:95], v[94:95], 0.5, v[100:101] op_sel_hi:[1,0,1]
	v_pk_fma_f32 v[92:93], v[92:93], 0.5, v[108:109] op_sel_hi:[1,0,1]
	v_pk_fma_f32 v[88:89], v[88:89], 0.5, v[110:111] op_sel_hi:[1,0,1]
	v_pk_fma_f32 v[84:85], v[84:85], 0.5, v[112:113] op_sel_hi:[1,0,1]
	v_mul_f32_e32 v112, v90, v90
	v_pk_fma_f32 v[86:87], v[86:87], 0.5, v[104:105] op_sel_hi:[1,0,1]
	v_pk_fma_f32 v[100:101], v[82:83], 0.5, v[106:107] op_sel_hi:[1,0,1]
	v_pk_fma_f32 v[102:103], v[80:81], 0.5, v[114:115] op_sel_hi:[1,0,1]
	v_cvt_pk_bf16_f32 v228, v92, v93
	v_cvt_pk_bf16_f32 v229, v94, v95
	v_add_f32_e32 v82, v92, v93
	v_add_f32_e32 v104, v94, v95
	v_mul_f32_e32 v107, v92, v92
	v_mul_f32_e32 v93, v93, v93
	v_mul_f32_e32 v109, v94, v94
	v_mul_f32_e32 v95, v95, v95
	v_cvt_pk_bf16_f32 v230, v88, v89
	v_mul_f32_e32 v83, v88, v88
	v_mul_f32_e32 v105, v89, v89
	v_mov_b32_e32 v106, v88
	v_mov_b32_e32 v92, v89
	v_mov_b32_e32 v108, v90
	v_mov_b32_e32 v94, v91
	v_pk_fma_f32 v[88:89], v[90:91], v[90:91], v[112:113] op_sel_hi:[1,1,0]
	v_cvt_pk_bf16_f32 v231, v90, v91
	v_mul_f32_e32 v115, v84, v84
	v_mul_f32_e32 v119, v85, v85
	v_mul_f32_e32 v121, v86, v86
	v_mul_f32_e32 v123, v87, v87
	v_mov_b32_e32 v114, v84
	v_mov_b32_e32 v118, v85
	v_mov_b32_e32 v120, v86
	v_mov_b32_e32 v122, v87
	v_pk_add_f32 v[90:91], v[106:107], v[92:93]
	v_pk_add_f32 v[92:93], v[108:109], v[94:95]
	v_pk_add_f32 v[82:83], v[82:83], v[104:105]
	v_mov_b32_e32 v133, v89
	v_mul_f32_e32 v125, v102, v102
	v_mul_f32_e32 v127, v103, v103
	v_mul_f32_e32 v159, v100, v100
	v_mul_f32_e32 v161, v101, v101
	v_mov_b32_e32 v124, v102
	v_mov_b32_e32 v126, v103
	v_mov_b32_e32 v158, v100
	v_mov_b32_e32 v160, v101
	v_pk_add_f32 v[94:95], v[114:115], v[118:119]
	v_pk_add_f32 v[104:105], v[120:121], v[122:123]
	v_pk_add_f32 v[90:91], v[90:91], v[92:93]
	v_pk_add_f32 v[82:83], v[82:83], v[132:133]
	v_pk_add_f32 v[106:107], v[124:125], v[126:127]
	v_pk_add_f32 v[108:109], v[158:159], v[160:161]
	v_pk_add_f32 v[88:89], v[94:95], v[104:105]
	v_pk_add_f32 v[82:83], v[90:91], v[82:83]
	v_pk_add_f32 v[92:93], v[106:107], v[108:109]
	v_pk_add_f32 v[82:83], v[82:83], v[88:89]
	s_nop 1
	v_permlane16_swap_b32_e32 v228, v230
	v_permlane16_swap_b32_e32 v229, v231
	v_lshl_add_u64 v[236:237], v[98:99], 0, v[238:239]
	global_store_dwordx4 v[236:237], v[228:231], off
	v_pk_add_f32 v[82:83], v[82:83], v[92:93]
	ds_bpermute_b32 v88, v156, v82
	ds_bpermute_b32 v89, v156, v83
	v_cvt_pk_bf16_f32 v232, v84, v85
	v_cvt_pk_bf16_f32 v233, v86, v87
	v_cvt_pk_bf16_f32 v234, v102, v103
	s_waitcnt lgkmcnt(0)
	v_pk_add_f32 v[80:81], v[82:83], v[88:89]
	ds_bpermute_b32 v82, v116, v80
	ds_bpermute_b32 v83, v116, v81
	v_cvt_pk_bf16_f32 v235, v100, v101
	s_nop 1
	v_permlane16_swap_b32_e32 v232, v234
	v_permlane16_swap_b32_e32 v233, v235
	global_store_dwordx4 v[236:237], v[232:235], off offset:256
	s_and_saveexec_b64 s[26:27], s[6:7]
	s_cbranch_execz .LBB0_277
	s_waitcnt lgkmcnt(0)
	v_pk_add_f32 v[80:81], v[80:81], v[82:83]
	v_and_b32_e32 v82, 0xff, v96
	v_bfe_u32 v83, v208, 6, 2
	v_lshlrev_b32_e32 v82, 5, v82
	v_lshl_add_u32 v82, v83, 3, v82
	v_add_u32_e32 v82, 0x20800, v82
	ds_write_b64 v82, v[80:81]
; #define GASP __attribute__((address_space(1)))
;     __device__ __forceinline__ void operator()(Acc& acc, const Unit& u, int wr, int wc, int fr, int fq, LAS unsigned char* lds) const {
;     ...
;                 const int rl = ai * HALF + wr * 64 + m * 16 + fr, row = u.pm * BM + rl;
;                 const float* rp = (row < split) ? res0 + (size_t)row * D : res1 + (size_t)(row - split) * D;
;                 float* op = out + (size_t)row * D;
;                 f32x2 st = (f32x2){0.f, 1.f}; if (STp) st = SL[rl];
;                 float s = 0.f, q = 0.f;
; #pragma unroll
;                 for (int bj = 0; bj < 2; ++bj)
; #pragma unroll
;                     for (int n = 0; n < 2; ++n) { const int c = col0 + bj * HALF + n * 16; f32x4 r;
;                         if (resb) { const u32x2 w = *(const GASP u32x2*)(resb + (size_t)row * D + c);
;                             r = (f32x4){__uint_as_float(w.x << 16), __uint_as_float(w.x & 0xffff0000u), __uint_as_float(w.y << 16), __uint_as_float(w.y & 0xffff0000u)}; }
;                         else r = *(const GASP f32x4*)(rp + c);
;                         if (STp) r = (r - st[0]) * st[1] * gg[bj][n] + bb[bj][n];
;                         const f32x4 o = r * ALPHA + acc[ai][bj][m][n] * scale;
;                         if (out) *(GASP f32x4*)(op + c) = o;
;                         if (ob) { u32x2 w; w.x = pk2(o[0], o[1]); w.y = pk2(o[2], o[3]); *(GASP u32x2*)(ob + (size_t)row * D + c) = w; }
;                         s += (o[0] + o[1]) + (o[2] + o[3]); q += (o[0] * o[0] + o[1] * o[1]) + (o[2] * o[2] + o[3] * o[3]); }
;                 if (STn) { s += __shfl_xor(s, 16); s += __shfl_xor(s, 32); q += __shfl_xor(q, 16); q += __shfl_xor(q, 32);
;                     if (fq == 0) *(GASP f32x2*)(STn + (size_t)row * 32 + (u.pn * 4 + wc) * 2) = (f32x2){s, q}; }
.LBB0_277:
	s_or_b64 exec, exec, s[26:27]
	v_add_u32_e32 v80, s28, v151
	v_ashrrev_i32_e32 v81, 31, v80
	v_cmp_gt_i32_e32 vcc, s41, v80
	s_nop 1
	v_cndmask_b32_e32 v81, 0, v81, vcc
	s_waitcnt lgkmcnt(0)
	v_lshlrev_b64 v[82:83], 11, v[80:81]
	v_lshl_add_u64 v[82:83], s[42:43], 0, v[82:83]
	v_lshl_add_u64 v[82:83], v[142:143], 1, v[82:83]
	global_load_dwordx2 v[84:85], v[82:83], off
	global_load_dwordx2 v[86:87], v[82:83], off offset:32
	global_load_dwordx2 v[88:89], v[82:83], off offset:256
	global_load_dwordx2 v[90:91], v[82:83], off offset:288
	s_waitcnt vmcnt(3)
	v_lshlrev_b32_e32 v92, 16, v84
	s_waitcnt vmcnt(2)
	v_lshlrev_b32_e32 v94, 16, v86
	v_and_b32_e32 v95, 0xffff0000, v86
	v_lshlrev_b32_e32 v86, 16, v87
	v_and_b32_e32 v87, 0xffff0000, v87
	v_and_b32_e32 v93, 0xffff0000, v84
	v_lshlrev_b32_e32 v84, 16, v85
	v_and_b32_e32 v85, 0xffff0000, v85
	s_waitcnt vmcnt(1)
	v_lshlrev_b32_e32 v96, 16, v88
	v_and_b32_e32 v97, 0xffff0000, v88
	v_pk_mul_f32 v[86:87], v[86:87], s[20:21] op_sel_hi:[1,0]
	v_lshlrev_b32_e32 v88, 16, v89
	v_and_b32_e32 v89, 0xffff0000, v89
	s_waitcnt vmcnt(0)
	v_lshlrev_b32_e32 v98, 16, v90
	v_and_b32_e32 v99, 0xffff0000, v90
	v_lshlrev_b32_e32 v90, 16, v91
	v_and_b32_e32 v91, 0xffff0000, v91
	v_pk_mul_f32 v[92:93], v[92:93], s[20:21] op_sel_hi:[1,0]
	v_pk_mul_f32 v[84:85], v[84:85], s[20:21] op_sel_hi:[1,0]
	v_pk_mul_f32 v[94:95], v[94:95], s[20:21] op_sel_hi:[1,0]
	v_pk_mul_f32 v[96:97], v[96:97], s[20:21] op_sel_hi:[1,0]
	v_pk_fma_f32 v[74:75], v[74:75], 0.5, v[86:87] op_sel_hi:[1,0,1]
	v_pk_mul_f32 v[88:89], v[88:89], s[20:21] op_sel_hi:[1,0]
	v_pk_mul_f32 v[98:99], v[98:99], s[20:21] op_sel_hi:[1,0]
	v_pk_mul_f32 v[90:91], v[90:91], s[20:21] op_sel_hi:[1,0]
	v_pk_fma_f32 v[78:79], v[78:79], 0.5, v[84:85] op_sel_hi:[1,0,1]
	v_pk_fma_f32 v[76:77], v[76:77], 0.5, v[92:93] op_sel_hi:[1,0,1]
	v_pk_fma_f32 v[72:73], v[72:73], 0.5, v[94:95] op_sel_hi:[1,0,1]
	v_pk_fma_f32 v[68:69], v[68:69], 0.5, v[96:97] op_sel_hi:[1,0,1]
	v_mul_f32_e32 v96, v74, v74
	v_pk_fma_f32 v[70:71], v[70:71], 0.5, v[88:89] op_sel_hi:[1,0,1]
	v_pk_fma_f32 v[84:85], v[66:67], 0.5, v[90:91] op_sel_hi:[1,0,1]
	v_pk_fma_f32 v[86:87], v[64:65], 0.5, v[98:99] op_sel_hi:[1,0,1]
	v_cvt_pk_bf16_f32 v228, v76, v77
	v_cvt_pk_bf16_f32 v229, v78, v79
	v_add_f32_e32 v66, v76, v77
	v_add_f32_e32 v88, v78, v79
	v_mul_f32_e32 v91, v76, v76
	v_mul_f32_e32 v77, v77, v77
	v_mul_f32_e32 v93, v78, v78
	v_mul_f32_e32 v79, v79, v79
	v_cvt_pk_bf16_f32 v230, v72, v73
	v_mul_f32_e32 v67, v72, v72
	v_mul_f32_e32 v89, v73, v73
	v_mov_b32_e32 v90, v72
	v_mov_b32_e32 v76, v73
	v_mov_b32_e32 v92, v74
	v_mov_b32_e32 v78, v75
	v_pk_fma_f32 v[72:73], v[74:75], v[74:75], v[96:97] op_sel_hi:[1,1,0]
	v_cvt_pk_bf16_f32 v231, v74, v75
	v_mul_f32_e32 v99, v68, v68
	v_mul_f32_e32 v101, v69, v69
	v_mul_f32_e32 v103, v70, v70
	v_mul_f32_e32 v105, v71, v71
	v_mov_b32_e32 v98, v68
	v_mov_b32_e32 v100, v69
	v_mov_b32_e32 v102, v70
	v_mov_b32_e32 v104, v71
	v_pk_add_f32 v[74:75], v[90:91], v[76:77]
	v_pk_add_f32 v[76:77], v[92:93], v[78:79]
	v_pk_add_f32 v[66:67], v[66:67], v[88:89]
	v_mov_b32_e32 v133, v73
	v_mul_f32_e32 v107, v86, v86
	v_mul_f32_e32 v109, v87, v87
	v_mul_f32_e32 v111, v84, v84
	v_mul_f32_e32 v113, v85, v85
	v_mov_b32_e32 v106, v86
	v_mov_b32_e32 v108, v87
	v_mov_b32_e32 v110, v84
	v_mov_b32_e32 v112, v85
	v_pk_add_f32 v[78:79], v[98:99], v[100:101]
	v_pk_add_f32 v[88:89], v[102:103], v[104:105]
	v_pk_add_f32 v[74:75], v[74:75], v[76:77]
	v_pk_add_f32 v[66:67], v[66:67], v[132:133]
	v_pk_add_f32 v[90:91], v[106:107], v[108:109]
	v_pk_add_f32 v[92:93], v[110:111], v[112:113]
	v_pk_add_f32 v[72:73], v[78:79], v[88:89]
	v_pk_add_f32 v[66:67], v[74:75], v[66:67]
	v_pk_add_f32 v[76:77], v[90:91], v[92:93]
	v_pk_add_f32 v[66:67], v[66:67], v[72:73]
	s_nop 1
	v_permlane16_swap_b32_e32 v228, v230
	v_permlane16_swap_b32_e32 v229, v231
	v_lshl_add_u64 v[236:237], v[82:83], 0, v[238:239]
	global_store_dwordx4 v[236:237], v[228:231], off
	v_pk_add_f32 v[66:67], v[66:67], v[76:77]
	ds_bpermute_b32 v72, v156, v66
	ds_bpermute_b32 v73, v156, v67
	v_cvt_pk_bf16_f32 v232, v68, v69
	v_cvt_pk_bf16_f32 v233, v70, v71
	v_cvt_pk_bf16_f32 v234, v86, v87
	s_waitcnt lgkmcnt(0)
	v_pk_add_f32 v[64:65], v[66:67], v[72:73]
	ds_bpermute_b32 v66, v116, v64
	ds_bpermute_b32 v67, v116, v65
	v_cvt_pk_bf16_f32 v235, v84, v85
	s_nop 1
	v_permlane16_swap_b32_e32 v232, v234
	v_permlane16_swap_b32_e32 v233, v235
	global_store_dwordx4 v[236:237], v[232:235], off offset:256
	s_and_saveexec_b64 s[26:27], s[6:7]
	s_cbranch_execz .LBB0_279
	s_waitcnt lgkmcnt(0)
	v_pk_add_f32 v[64:65], v[64:65], v[66:67]
	v_and_b32_e32 v66, 0xff, v80
	v_bfe_u32 v67, v208, 6, 2
	v_lshlrev_b32_e32 v66, 5, v66
	v_lshl_add_u32 v66, v67, 3, v66
	v_add_u32_e32 v66, 0x20800, v66
	ds_write_b64 v66, v[64:65]
; #define GASP __attribute__((address_space(1)))
;     __device__ __forceinline__ void operator()(Acc& acc, const Unit& u, int wr, int wc, int fr, int fq, LAS unsigned char* lds) const {
;     ...
;                 const int rl = ai * HALF + wr * 64 + m * 16 + fr, row = u.pm * BM + rl;
;                 const float* rp = (row < split) ? res0 + (size_t)row * D : res1 + (size_t)(row - split) * D;
;                 float* op = out + (size_t)row * D;
;                 f32x2 st = (f32x2){0.f, 1.f}; if (STp) st = SL[rl];
;                 float s = 0.f, q = 0.f;
; #pragma unroll
;                 for (int bj = 0; bj < 2; ++bj)
; #pragma unroll
;                     for (int n = 0; n < 2; ++n) { const int c = col0 + bj * HALF + n * 16; f32x4 r;
;                         if (resb) { const u32x2 w = *(const GASP u32x2*)(resb + (size_t)row * D + c);
;                             r = (f32x4){__uint_as_float(w.x << 16), __uint_as_float(w.x & 0xffff0000u), __uint_as_float(w.y << 16), __uint_as_float(w.y & 0xffff0000u)}; }
;                         else r = *(const GASP f32x4*)(rp + c);
;                         if (STp) r = (r - st[0]) * st[1] * gg[bj][n] + bb[bj][n];
;                         const f32x4 o = r * ALPHA + acc[ai][bj][m][n] * scale;
;                         if (out) *(GASP f32x4*)(op + c) = o;
;                         if (ob) { u32x2 w; w.x = pk2(o[0], o[1]); w.y = pk2(o[2], o[3]); *(GASP u32x2*)(ob + (size_t)row * D + c) = w; }
;                         s += (o[0] + o[1]) + (o[2] + o[3]); q += (o[0] * o[0] + o[1] * o[1]) + (o[2] * o[2] + o[3] * o[3]); }
;                 if (STn) { s += __shfl_xor(s, 16); s += __shfl_xor(s, 32); q += __shfl_xor(q, 16); q += __shfl_xor(q, 32);
;                     if (fq == 0) *(GASP f32x2*)(STn + (size_t)row * 32 + (u.pn * 4 + wc) * 2) = (f32x2){s, q}; }
.LBB0_279:
	s_or_b64 exec, exec, s[26:27]
	v_add_u32_e32 v64, 0x80, v144
	v_ashrrev_i32_e32 v65, 31, v64
	v_cmp_gt_i32_e32 vcc, s41, v64
	s_nop 1
	v_cndmask_b32_e32 v65, 0, v65, vcc
	s_waitcnt lgkmcnt(0)
	v_lshlrev_b64 v[66:67], 11, v[64:65]
	v_lshl_add_u64 v[66:67], s[42:43], 0, v[66:67]
	v_lshl_add_u64 v[66:67], v[142:143], 1, v[66:67]
	global_load_dwordx2 v[68:69], v[66:67], off
	global_load_dwordx2 v[70:71], v[66:67], off offset:32
	global_load_dwordx2 v[72:73], v[66:67], off offset:256
	global_load_dwordx2 v[74:75], v[66:67], off offset:288
	s_waitcnt vmcnt(3)
	v_lshlrev_b32_e32 v76, 16, v68
	s_waitcnt vmcnt(2)
	v_lshlrev_b32_e32 v78, 16, v70
	v_and_b32_e32 v79, 0xffff0000, v70
	v_lshlrev_b32_e32 v70, 16, v71
	v_and_b32_e32 v71, 0xffff0000, v71
	v_and_b32_e32 v77, 0xffff0000, v68
	v_lshlrev_b32_e32 v68, 16, v69
	v_and_b32_e32 v69, 0xffff0000, v69
	s_waitcnt vmcnt(1)
	v_lshlrev_b32_e32 v80, 16, v72
	v_and_b32_e32 v81, 0xffff0000, v72
	v_pk_mul_f32 v[70:71], v[70:71], s[20:21] op_sel_hi:[1,0]
	v_lshlrev_b32_e32 v72, 16, v73
	v_and_b32_e32 v73, 0xffff0000, v73
	s_waitcnt vmcnt(0)
	v_lshlrev_b32_e32 v82, 16, v74
	v_and_b32_e32 v83, 0xffff0000, v74
	v_lshlrev_b32_e32 v74, 16, v75
	v_and_b32_e32 v75, 0xffff0000, v75
	v_pk_mul_f32 v[76:77], v[76:77], s[20:21] op_sel_hi:[1,0]
	v_pk_mul_f32 v[68:69], v[68:69], s[20:21] op_sel_hi:[1,0]
	v_pk_mul_f32 v[78:79], v[78:79], s[20:21] op_sel_hi:[1,0]
	v_pk_mul_f32 v[80:81], v[80:81], s[20:21] op_sel_hi:[1,0]
	v_pk_fma_f32 v[58:59], v[58:59], 0.5, v[70:71] op_sel_hi:[1,0,1]
	v_pk_mul_f32 v[72:73], v[72:73], s[20:21] op_sel_hi:[1,0]
	v_pk_mul_f32 v[82:83], v[82:83], s[20:21] op_sel_hi:[1,0]
	v_pk_mul_f32 v[74:75], v[74:75], s[20:21] op_sel_hi:[1,0]
	v_pk_fma_f32 v[62:63], v[62:63], 0.5, v[68:69] op_sel_hi:[1,0,1]
	v_pk_fma_f32 v[60:61], v[60:61], 0.5, v[76:77] op_sel_hi:[1,0,1]
	v_pk_fma_f32 v[56:57], v[56:57], 0.5, v[78:79] op_sel_hi:[1,0,1]
	v_pk_fma_f32 v[52:53], v[52:53], 0.5, v[80:81] op_sel_hi:[1,0,1]
	v_mul_f32_e32 v80, v58, v58
	v_pk_fma_f32 v[54:55], v[54:55], 0.5, v[72:73] op_sel_hi:[1,0,1]
	v_pk_fma_f32 v[68:69], v[50:51], 0.5, v[74:75] op_sel_hi:[1,0,1]
	v_pk_fma_f32 v[70:71], v[48:49], 0.5, v[82:83] op_sel_hi:[1,0,1]
	v_cvt_pk_bf16_f32 v228, v60, v61
	v_cvt_pk_bf16_f32 v229, v62, v63
	v_add_f32_e32 v50, v60, v61
	v_add_f32_e32 v72, v62, v63
	v_mul_f32_e32 v75, v60, v60
	v_mul_f32_e32 v61, v61, v61
	v_mul_f32_e32 v77, v62, v62
	v_mul_f32_e32 v63, v63, v63
	v_cvt_pk_bf16_f32 v230, v56, v57
	v_mul_f32_e32 v51, v56, v56
	v_mul_f32_e32 v73, v57, v57
	v_mov_b32_e32 v74, v56
	v_mov_b32_e32 v60, v57
	v_mov_b32_e32 v76, v58
	v_mov_b32_e32 v62, v59
	v_pk_fma_f32 v[56:57], v[58:59], v[58:59], v[80:81] op_sel_hi:[1,1,0]
	v_cvt_pk_bf16_f32 v231, v58, v59
	v_mul_f32_e32 v83, v52, v52
	v_mul_f32_e32 v85, v53, v53
	v_mul_f32_e32 v87, v54, v54
	v_mul_f32_e32 v89, v55, v55
	v_mov_b32_e32 v82, v52
	v_mov_b32_e32 v84, v53
	v_mov_b32_e32 v86, v54
	v_mov_b32_e32 v88, v55
	v_pk_add_f32 v[58:59], v[74:75], v[60:61]
	v_pk_add_f32 v[60:61], v[76:77], v[62:63]
	v_pk_add_f32 v[50:51], v[50:51], v[72:73]
	v_mov_b32_e32 v133, v57
	v_mul_f32_e32 v91, v70, v70
	v_mul_f32_e32 v93, v71, v71
	v_mul_f32_e32 v95, v68, v68
	v_mul_f32_e32 v97, v69, v69
	v_mov_b32_e32 v90, v70
	v_mov_b32_e32 v92, v71
	v_mov_b32_e32 v94, v68
	v_mov_b32_e32 v96, v69
	v_pk_add_f32 v[62:63], v[82:83], v[84:85]
	v_pk_add_f32 v[72:73], v[86:87], v[88:89]
	v_pk_add_f32 v[58:59], v[58:59], v[60:61]
	v_pk_add_f32 v[50:51], v[50:51], v[132:133]
	v_pk_add_f32 v[74:75], v[90:91], v[92:93]
	v_pk_add_f32 v[76:77], v[94:95], v[96:97]
	v_pk_add_f32 v[56:57], v[62:63], v[72:73]
	v_pk_add_f32 v[50:51], v[58:59], v[50:51]
	v_pk_add_f32 v[60:61], v[74:75], v[76:77]
	v_pk_add_f32 v[50:51], v[50:51], v[56:57]
	s_nop 1
	v_permlane16_swap_b32_e32 v228, v230
	v_permlane16_swap_b32_e32 v229, v231
	v_lshl_add_u64 v[236:237], v[66:67], 0, v[238:239]
	global_store_dwordx4 v[236:237], v[228:231], off
	v_pk_add_f32 v[50:51], v[50:51], v[60:61]
	ds_bpermute_b32 v56, v156, v50
	ds_bpermute_b32 v57, v156, v51
	v_cvt_pk_bf16_f32 v232, v52, v53
	v_cvt_pk_bf16_f32 v233, v54, v55
	v_cvt_pk_bf16_f32 v234, v70, v71
	s_waitcnt lgkmcnt(0)
	v_pk_add_f32 v[48:49], v[50:51], v[56:57]
	ds_bpermute_b32 v50, v116, v48
	ds_bpermute_b32 v51, v116, v49
	v_cvt_pk_bf16_f32 v235, v68, v69
	s_nop 1
	v_permlane16_swap_b32_e32 v232, v234
	v_permlane16_swap_b32_e32 v233, v235
	global_store_dwordx4 v[236:237], v[232:235], off offset:256
	s_and_saveexec_b64 s[26:27], s[6:7]
	s_cbranch_execz .LBB0_281
	s_waitcnt lgkmcnt(0)
	v_pk_add_f32 v[48:49], v[48:49], v[50:51]
	v_and_b32_e32 v50, 0xff, v64
	v_bfe_u32 v51, v208, 6, 2
	v_lshlrev_b32_e32 v50, 5, v50
	v_lshl_add_u32 v50, v51, 3, v50
	v_add_u32_e32 v50, 0x20800, v50
	ds_write_b64 v50, v[48:49]
; #define GASP __attribute__((address_space(1)))
;     __device__ __forceinline__ void operator()(Acc& acc, const Unit& u, int wr, int wc, int fr, int fq, LAS unsigned char* lds) const {
;     ...
;                 const int rl = ai * HALF + wr * 64 + m * 16 + fr, row = u.pm * BM + rl;
;                 const float* rp = (row < split) ? res0 + (size_t)row * D : res1 + (size_t)(row - split) * D;
;                 float* op = out + (size_t)row * D;
;                 f32x2 st = (f32x2){0.f, 1.f}; if (STp) st = SL[rl];
;                 float s = 0.f, q = 0.f;
; #pragma unroll
;                 for (int bj = 0; bj < 2; ++bj)
; #pragma unroll
;                     for (int n = 0; n < 2; ++n) { const int c = col0 + bj * HALF + n * 16; f32x4 r;
;                         if (resb) { const u32x2 w = *(const GASP u32x2*)(resb + (size_t)row * D + c);
;                             r = (f32x4){__uint_as_float(w.x << 16), __uint_as_float(w.x & 0xffff0000u), __uint_as_float(w.y << 16), __uint_as_float(w.y & 0xffff0000u)}; }
;                         else r = *(const GASP f32x4*)(rp + c);
;                         if (STp) r = (r - st[0]) * st[1] * gg[bj][n] + bb[bj][n];
;                         const f32x4 o = r * ALPHA + acc[ai][bj][m][n] * scale;
;                         if (out) *(GASP f32x4*)(op + c) = o;
;                         if (ob) { u32x2 w; w.x = pk2(o[0], o[1]); w.y = pk2(o[2], o[3]); *(GASP u32x2*)(ob + (size_t)row * D + c) = w; }
;                         s += (o[0] + o[1]) + (o[2] + o[3]); q += (o[0] * o[0] + o[1] * o[1]) + (o[2] * o[2] + o[3] * o[3]); }
;                 if (STn) { s += __shfl_xor(s, 16); s += __shfl_xor(s, 32); q += __shfl_xor(q, 16); q += __shfl_xor(q, 32);
;                     if (fq == 0) *(GASP f32x2*)(STn + (size_t)row * 32 + (u.pn * 4 + wc) * 2) = (f32x2){s, q}; }
.LBB0_281:
	s_or_b64 exec, exec, s[26:27]
	v_add_u32_e32 v48, 0x90, v144
	v_ashrrev_i32_e32 v49, 31, v48
	v_cmp_gt_i32_e32 vcc, s41, v48
	s_nop 1
	v_cndmask_b32_e32 v49, 0, v49, vcc
	s_waitcnt lgkmcnt(0)
	v_lshlrev_b64 v[50:51], 11, v[48:49]
	v_lshl_add_u64 v[50:51], s[42:43], 0, v[50:51]
	v_lshl_add_u64 v[50:51], v[142:143], 1, v[50:51]
	global_load_dwordx2 v[52:53], v[50:51], off
	global_load_dwordx2 v[54:55], v[50:51], off offset:32
	global_load_dwordx2 v[56:57], v[50:51], off offset:256
	global_load_dwordx2 v[58:59], v[50:51], off offset:288
	s_waitcnt vmcnt(3)
	v_lshlrev_b32_e32 v60, 16, v52
	s_waitcnt vmcnt(2)
	v_lshlrev_b32_e32 v62, 16, v54
	v_and_b32_e32 v63, 0xffff0000, v54
	v_lshlrev_b32_e32 v54, 16, v55
	v_and_b32_e32 v55, 0xffff0000, v55
	v_and_b32_e32 v61, 0xffff0000, v52
	v_lshlrev_b32_e32 v52, 16, v53
	v_and_b32_e32 v53, 0xffff0000, v53
	s_waitcnt vmcnt(1)
	v_lshlrev_b32_e32 v64, 16, v56
	v_and_b32_e32 v65, 0xffff0000, v56
	v_pk_mul_f32 v[54:55], v[54:55], s[20:21] op_sel_hi:[1,0]
	v_lshlrev_b32_e32 v56, 16, v57
	v_and_b32_e32 v57, 0xffff0000, v57
	s_waitcnt vmcnt(0)
	v_lshlrev_b32_e32 v66, 16, v58
	v_and_b32_e32 v67, 0xffff0000, v58
	v_lshlrev_b32_e32 v58, 16, v59
	v_and_b32_e32 v59, 0xffff0000, v59
	v_pk_mul_f32 v[60:61], v[60:61], s[20:21] op_sel_hi:[1,0]
	v_pk_mul_f32 v[52:53], v[52:53], s[20:21] op_sel_hi:[1,0]
	v_pk_mul_f32 v[62:63], v[62:63], s[20:21] op_sel_hi:[1,0]
	v_pk_mul_f32 v[64:65], v[64:65], s[20:21] op_sel_hi:[1,0]
	v_pk_fma_f32 v[42:43], v[42:43], 0.5, v[54:55] op_sel_hi:[1,0,1]
	v_pk_mul_f32 v[56:57], v[56:57], s[20:21] op_sel_hi:[1,0]
	v_pk_mul_f32 v[66:67], v[66:67], s[20:21] op_sel_hi:[1,0]
	v_pk_mul_f32 v[58:59], v[58:59], s[20:21] op_sel_hi:[1,0]
	v_pk_fma_f32 v[46:47], v[46:47], 0.5, v[52:53] op_sel_hi:[1,0,1]
	v_pk_fma_f32 v[44:45], v[44:45], 0.5, v[60:61] op_sel_hi:[1,0,1]
	v_pk_fma_f32 v[40:41], v[40:41], 0.5, v[62:63] op_sel_hi:[1,0,1]
	v_pk_fma_f32 v[36:37], v[36:37], 0.5, v[64:65] op_sel_hi:[1,0,1]
	v_mul_f32_e32 v64, v42, v42
	v_pk_fma_f32 v[38:39], v[38:39], 0.5, v[56:57] op_sel_hi:[1,0,1]
	v_pk_fma_f32 v[52:53], v[34:35], 0.5, v[58:59] op_sel_hi:[1,0,1]
	v_pk_fma_f32 v[54:55], v[32:33], 0.5, v[66:67] op_sel_hi:[1,0,1]
	v_cvt_pk_bf16_f32 v228, v44, v45
	v_cvt_pk_bf16_f32 v229, v46, v47
	v_add_f32_e32 v34, v44, v45
	v_add_f32_e32 v56, v46, v47
	v_mul_f32_e32 v59, v44, v44
	v_mul_f32_e32 v45, v45, v45
	v_mul_f32_e32 v61, v46, v46
	v_mul_f32_e32 v47, v47, v47
	v_cvt_pk_bf16_f32 v230, v40, v41
	v_mul_f32_e32 v35, v40, v40
	v_mul_f32_e32 v57, v41, v41
	v_mov_b32_e32 v58, v40
	v_mov_b32_e32 v44, v41
	v_mov_b32_e32 v60, v42
	v_mov_b32_e32 v46, v43
	v_pk_fma_f32 v[40:41], v[42:43], v[42:43], v[64:65] op_sel_hi:[1,1,0]
	v_cvt_pk_bf16_f32 v231, v42, v43
	v_mul_f32_e32 v67, v36, v36
	v_mul_f32_e32 v69, v37, v37
	v_mul_f32_e32 v71, v38, v38
	v_mul_f32_e32 v73, v39, v39
	v_mov_b32_e32 v66, v36
	v_mov_b32_e32 v68, v37
	v_mov_b32_e32 v70, v38
	v_mov_b32_e32 v72, v39
	v_pk_add_f32 v[42:43], v[58:59], v[44:45]
	v_pk_add_f32 v[44:45], v[60:61], v[46:47]
	v_pk_add_f32 v[34:35], v[34:35], v[56:57]
	v_mov_b32_e32 v133, v41
	v_mul_f32_e32 v75, v54, v54
	v_mul_f32_e32 v77, v55, v55
	v_mul_f32_e32 v79, v52, v52
	v_mul_f32_e32 v81, v53, v53
	v_mov_b32_e32 v74, v54
	v_mov_b32_e32 v76, v55
	v_mov_b32_e32 v78, v52
	v_mov_b32_e32 v80, v53
	v_pk_add_f32 v[46:47], v[66:67], v[68:69]
	v_pk_add_f32 v[56:57], v[70:71], v[72:73]
	v_pk_add_f32 v[42:43], v[42:43], v[44:45]
	v_pk_add_f32 v[34:35], v[34:35], v[132:133]
	v_pk_add_f32 v[58:59], v[74:75], v[76:77]
	v_pk_add_f32 v[60:61], v[78:79], v[80:81]
	v_pk_add_f32 v[40:41], v[46:47], v[56:57]
	v_pk_add_f32 v[34:35], v[42:43], v[34:35]
	v_pk_add_f32 v[44:45], v[58:59], v[60:61]
	v_pk_add_f32 v[34:35], v[34:35], v[40:41]
	s_nop 1
	v_permlane16_swap_b32_e32 v228, v230
	v_permlane16_swap_b32_e32 v229, v231
	v_lshl_add_u64 v[236:237], v[50:51], 0, v[238:239]
	global_store_dwordx4 v[236:237], v[228:231], off
	v_pk_add_f32 v[34:35], v[34:35], v[44:45]
	ds_bpermute_b32 v40, v156, v34
	ds_bpermute_b32 v41, v156, v35
	v_cvt_pk_bf16_f32 v232, v36, v37
	v_cvt_pk_bf16_f32 v233, v38, v39
	v_cvt_pk_bf16_f32 v234, v54, v55
	s_waitcnt lgkmcnt(0)
	v_pk_add_f32 v[32:33], v[34:35], v[40:41]
	ds_bpermute_b32 v34, v116, v32
	ds_bpermute_b32 v35, v116, v33
	v_cvt_pk_bf16_f32 v235, v52, v53
	s_nop 1
	v_permlane16_swap_b32_e32 v232, v234
	v_permlane16_swap_b32_e32 v233, v235
	global_store_dwordx4 v[236:237], v[232:235], off offset:256
	s_and_saveexec_b64 s[26:27], s[6:7]
	s_cbranch_execz .LBB0_283
	s_waitcnt lgkmcnt(0)
	v_pk_add_f32 v[32:33], v[32:33], v[34:35]
	v_and_b32_e32 v34, 0xff, v48
	v_bfe_u32 v35, v208, 6, 2
	v_lshlrev_b32_e32 v34, 5, v34
	v_lshl_add_u32 v34, v35, 3, v34
	v_add_u32_e32 v34, 0x20800, v34
	ds_write_b64 v34, v[32:33]
; #define GASP __attribute__((address_space(1)))
;     __device__ __forceinline__ void operator()(Acc& acc, const Unit& u, int wr, int wc, int fr, int fq, LAS unsigned char* lds) const {
;     ...
;                 const int rl = ai * HALF + wr * 64 + m * 16 + fr, row = u.pm * BM + rl;
;                 const float* rp = (row < split) ? res0 + (size_t)row * D : res1 + (size_t)(row - split) * D;
;                 float* op = out + (size_t)row * D;
;                 f32x2 st = (f32x2){0.f, 1.f}; if (STp) st = SL[rl];
;                 float s = 0.f, q = 0.f;
; #pragma unroll
;                 for (int bj = 0; bj < 2; ++bj)
; #pragma unroll
;                     for (int n = 0; n < 2; ++n) { const int c = col0 + bj * HALF + n * 16; f32x4 r;
;                         if (resb) { const u32x2 w = *(const GASP u32x2*)(resb + (size_t)row * D + c);
;                             r = (f32x4){__uint_as_float(w.x << 16), __uint_as_float(w.x & 0xffff0000u), __uint_as_float(w.y << 16), __uint_as_float(w.y & 0xffff0000u)}; }
;                         else r = *(const GASP f32x4*)(rp + c);
;                         if (STp) r = (r - st[0]) * st[1] * gg[bj][n] + bb[bj][n];
;                         const f32x4 o = r * ALPHA + acc[ai][bj][m][n] * scale;
;                         if (out) *(GASP f32x4*)(op + c) = o;
;                         if (ob) { u32x2 w; w.x = pk2(o[0], o[1]); w.y = pk2(o[2], o[3]); *(GASP u32x2*)(ob + (size_t)row * D + c) = w; }
;                         s += (o[0] + o[1]) + (o[2] + o[3]); q += (o[0] * o[0] + o[1] * o[1]) + (o[2] * o[2] + o[3] * o[3]); }
;                 if (STn) { s += __shfl_xor(s, 16); s += __shfl_xor(s, 32); q += __shfl_xor(q, 16); q += __shfl_xor(q, 32);
;                     if (fq == 0) *(GASP f32x2*)(STn + (size_t)row * 32 + (u.pn * 4 + wc) * 2) = (f32x2){s, q}; }
.LBB0_283:
	s_or_b64 exec, exec, s[26:27]
	v_add_u32_e32 v32, 0xa0, v144
	v_ashrrev_i32_e32 v33, 31, v32
	v_cmp_gt_i32_e32 vcc, s41, v32
	s_nop 1
	v_cndmask_b32_e32 v33, 0, v33, vcc
	s_waitcnt lgkmcnt(0)
	v_lshlrev_b64 v[34:35], 11, v[32:33]
	v_lshl_add_u64 v[34:35], s[42:43], 0, v[34:35]
	v_lshl_add_u64 v[34:35], v[142:143], 1, v[34:35]
	global_load_dwordx2 v[36:37], v[34:35], off
	global_load_dwordx2 v[38:39], v[34:35], off offset:32
	global_load_dwordx2 v[40:41], v[34:35], off offset:256
	global_load_dwordx2 v[42:43], v[34:35], off offset:288
	s_waitcnt vmcnt(3)
	v_lshlrev_b32_e32 v44, 16, v36
	s_waitcnt vmcnt(2)
	v_lshlrev_b32_e32 v46, 16, v38
	v_and_b32_e32 v47, 0xffff0000, v38
	v_lshlrev_b32_e32 v38, 16, v39
	v_and_b32_e32 v39, 0xffff0000, v39
	v_and_b32_e32 v45, 0xffff0000, v36
	v_lshlrev_b32_e32 v36, 16, v37
	v_and_b32_e32 v37, 0xffff0000, v37
	s_waitcnt vmcnt(1)
	v_lshlrev_b32_e32 v48, 16, v40
	v_and_b32_e32 v49, 0xffff0000, v40
	v_pk_mul_f32 v[38:39], v[38:39], s[20:21] op_sel_hi:[1,0]
	v_lshlrev_b32_e32 v40, 16, v41
	v_and_b32_e32 v41, 0xffff0000, v41
	s_waitcnt vmcnt(0)
	v_lshlrev_b32_e32 v50, 16, v42
	v_and_b32_e32 v51, 0xffff0000, v42
	v_lshlrev_b32_e32 v42, 16, v43
	v_and_b32_e32 v43, 0xffff0000, v43
	v_pk_mul_f32 v[44:45], v[44:45], s[20:21] op_sel_hi:[1,0]
	v_pk_mul_f32 v[36:37], v[36:37], s[20:21] op_sel_hi:[1,0]
	v_pk_mul_f32 v[46:47], v[46:47], s[20:21] op_sel_hi:[1,0]
	v_pk_mul_f32 v[48:49], v[48:49], s[20:21] op_sel_hi:[1,0]
	v_pk_fma_f32 v[26:27], v[26:27], 0.5, v[38:39] op_sel_hi:[1,0,1]
	v_pk_mul_f32 v[40:41], v[40:41], s[20:21] op_sel_hi:[1,0]
	v_pk_mul_f32 v[50:51], v[50:51], s[20:21] op_sel_hi:[1,0]
	v_pk_mul_f32 v[42:43], v[42:43], s[20:21] op_sel_hi:[1,0]
	v_pk_fma_f32 v[30:31], v[30:31], 0.5, v[36:37] op_sel_hi:[1,0,1]
	v_pk_fma_f32 v[28:29], v[28:29], 0.5, v[44:45] op_sel_hi:[1,0,1]
	v_pk_fma_f32 v[24:25], v[24:25], 0.5, v[46:47] op_sel_hi:[1,0,1]
	v_pk_fma_f32 v[20:21], v[20:21], 0.5, v[48:49] op_sel_hi:[1,0,1]
	v_mul_f32_e32 v48, v26, v26
	v_pk_fma_f32 v[22:23], v[22:23], 0.5, v[40:41] op_sel_hi:[1,0,1]
	v_pk_fma_f32 v[36:37], v[18:19], 0.5, v[42:43] op_sel_hi:[1,0,1]
	v_pk_fma_f32 v[38:39], v[16:17], 0.5, v[50:51] op_sel_hi:[1,0,1]
	v_cvt_pk_bf16_f32 v228, v28, v29
	v_cvt_pk_bf16_f32 v229, v30, v31
	v_add_f32_e32 v18, v28, v29
	v_add_f32_e32 v40, v30, v31
	v_mul_f32_e32 v43, v28, v28
	v_mul_f32_e32 v29, v29, v29
	v_mul_f32_e32 v45, v30, v30
	v_mul_f32_e32 v31, v31, v31
	v_cvt_pk_bf16_f32 v230, v24, v25
	v_mul_f32_e32 v19, v24, v24
	v_mul_f32_e32 v41, v25, v25
	v_mov_b32_e32 v42, v24
	v_mov_b32_e32 v28, v25
	v_mov_b32_e32 v44, v26
	v_mov_b32_e32 v30, v27
	v_pk_fma_f32 v[24:25], v[26:27], v[26:27], v[48:49] op_sel_hi:[1,1,0]
	v_cvt_pk_bf16_f32 v231, v26, v27
	v_mul_f32_e32 v51, v20, v20
	v_mul_f32_e32 v53, v21, v21
	v_mul_f32_e32 v55, v22, v22
	v_mul_f32_e32 v57, v23, v23
	v_mov_b32_e32 v50, v20
	v_mov_b32_e32 v52, v21
	v_mov_b32_e32 v54, v22
	v_mov_b32_e32 v56, v23
	v_pk_add_f32 v[26:27], v[42:43], v[28:29]
	v_pk_add_f32 v[28:29], v[44:45], v[30:31]
	v_pk_add_f32 v[18:19], v[18:19], v[40:41]
	v_mov_b32_e32 v133, v25
	v_mul_f32_e32 v59, v38, v38
	v_mul_f32_e32 v61, v39, v39
	v_mul_f32_e32 v63, v36, v36
	v_mul_f32_e32 v65, v37, v37
	v_mov_b32_e32 v58, v38
	v_mov_b32_e32 v60, v39
	v_mov_b32_e32 v62, v36
	v_mov_b32_e32 v64, v37
	v_pk_add_f32 v[30:31], v[50:51], v[52:53]
	v_pk_add_f32 v[40:41], v[54:55], v[56:57]
	v_pk_add_f32 v[26:27], v[26:27], v[28:29]
	v_pk_add_f32 v[18:19], v[18:19], v[132:133]
	v_pk_add_f32 v[42:43], v[58:59], v[60:61]
	v_pk_add_f32 v[44:45], v[62:63], v[64:65]
	v_pk_add_f32 v[24:25], v[30:31], v[40:41]
	v_pk_add_f32 v[18:19], v[26:27], v[18:19]
	v_pk_add_f32 v[28:29], v[42:43], v[44:45]
	v_pk_add_f32 v[18:19], v[18:19], v[24:25]
	s_nop 1
	v_permlane16_swap_b32_e32 v228, v230
	v_permlane16_swap_b32_e32 v229, v231
	v_lshl_add_u64 v[236:237], v[34:35], 0, v[238:239]
	global_store_dwordx4 v[236:237], v[228:231], off
	v_pk_add_f32 v[18:19], v[18:19], v[28:29]
	ds_bpermute_b32 v24, v156, v18
	ds_bpermute_b32 v25, v156, v19
	v_cvt_pk_bf16_f32 v232, v20, v21
	v_cvt_pk_bf16_f32 v233, v22, v23
	v_cvt_pk_bf16_f32 v234, v38, v39
	s_waitcnt lgkmcnt(0)
	v_pk_add_f32 v[16:17], v[18:19], v[24:25]
	ds_bpermute_b32 v18, v116, v16
	ds_bpermute_b32 v19, v116, v17
	v_cvt_pk_bf16_f32 v235, v36, v37
	s_nop 1
	v_permlane16_swap_b32_e32 v232, v234
	v_permlane16_swap_b32_e32 v233, v235
	global_store_dwordx4 v[236:237], v[232:235], off offset:256
	s_and_saveexec_b64 s[26:27], s[6:7]
	s_cbranch_execz .LBB0_285
	s_waitcnt lgkmcnt(0)
	v_pk_add_f32 v[16:17], v[16:17], v[18:19]
	v_and_b32_e32 v18, 0xff, v32
	v_bfe_u32 v19, v208, 6, 2
	v_lshlrev_b32_e32 v18, 5, v18
	v_lshl_add_u32 v18, v19, 3, v18
	v_add_u32_e32 v18, 0x20800, v18
	ds_write_b64 v18, v[16:17]
; #define GASP __attribute__((address_space(1)))
;     __device__ __forceinline__ void operator()(Acc& acc, const Unit& u, int wr, int wc, int fr, int fq, LAS unsigned char* lds) const {
;     ...
;                 const int rl = ai * HALF + wr * 64 + m * 16 + fr, row = u.pm * BM + rl;
;                 const float* rp = (row < split) ? res0 + (size_t)row * D : res1 + (size_t)(row - split) * D;
;                 float* op = out + (size_t)row * D;
;                 f32x2 st = (f32x2){0.f, 1.f}; if (STp) st = SL[rl];
;                 float s = 0.f, q = 0.f;
; #pragma unroll
;                 for (int bj = 0; bj < 2; ++bj)
; #pragma unroll
;                     for (int n = 0; n < 2; ++n) { const int c = col0 + bj * HALF + n * 16; f32x4 r;
;                         if (resb) { const u32x2 w = *(const GASP u32x2*)(resb + (size_t)row * D + c);
;                             r = (f32x4){__uint_as_float(w.x << 16), __uint_as_float(w.x & 0xffff0000u), __uint_as_float(w.y << 16), __uint_as_float(w.y & 0xffff0000u)}; }
;                         else r = *(const GASP f32x4*)(rp + c);
;                         if (STp) r = (r - st[0]) * st[1] * gg[bj][n] + bb[bj][n];
;                         const f32x4 o = r * ALPHA + acc[ai][bj][m][n] * scale;
;                         if (out) *(GASP f32x4*)(op + c) = o;
;                         if (ob) { u32x2 w; w.x = pk2(o[0], o[1]); w.y = pk2(o[2], o[3]); *(GASP u32x2*)(ob + (size_t)row * D + c) = w; }
;                         s += (o[0] + o[1]) + (o[2] + o[3]); q += (o[0] * o[0] + o[1] * o[1]) + (o[2] * o[2] + o[3] * o[3]); }
;                 if (STn) { s += __shfl_xor(s, 16); s += __shfl_xor(s, 32); q += __shfl_xor(q, 16); q += __shfl_xor(q, 32);
;                     if (fq == 0) *(GASP f32x2*)(STn + (size_t)row * 32 + (u.pn * 4 + wc) * 2) = (f32x2){s, q}; }
.LBB0_285:
	s_or_b64 exec, exec, s[26:27]
	v_add_u32_e32 v16, 0xb0, v144
	v_ashrrev_i32_e32 v17, 31, v16
	v_cmp_gt_i32_e32 vcc, s41, v16
	s_nop 1
	v_cndmask_b32_e32 v17, 0, v17, vcc
	s_waitcnt lgkmcnt(0)
	v_lshlrev_b64 v[18:19], 11, v[16:17]
	v_lshl_add_u64 v[18:19], s[42:43], 0, v[18:19]
	v_lshl_add_u64 v[18:19], v[142:143], 1, v[18:19]
	global_load_dwordx2 v[20:21], v[18:19], off
	global_load_dwordx2 v[22:23], v[18:19], off offset:32
	global_load_dwordx2 v[24:25], v[18:19], off offset:256
	global_load_dwordx2 v[26:27], v[18:19], off offset:288
	s_waitcnt vmcnt(3)
	v_lshlrev_b32_e32 v28, 16, v20
	s_waitcnt vmcnt(2)
	v_lshlrev_b32_e32 v30, 16, v22
	v_and_b32_e32 v31, 0xffff0000, v22
	v_lshlrev_b32_e32 v22, 16, v23
	v_and_b32_e32 v23, 0xffff0000, v23
	v_and_b32_e32 v29, 0xffff0000, v20
	v_lshlrev_b32_e32 v20, 16, v21
	v_and_b32_e32 v21, 0xffff0000, v21
	s_waitcnt vmcnt(1)
	v_lshlrev_b32_e32 v32, 16, v24
	v_and_b32_e32 v33, 0xffff0000, v24
	v_pk_mul_f32 v[22:23], v[22:23], s[20:21] op_sel_hi:[1,0]
	v_lshlrev_b32_e32 v24, 16, v25
	v_and_b32_e32 v25, 0xffff0000, v25
	s_waitcnt vmcnt(0)
	v_lshlrev_b32_e32 v34, 16, v26
	v_and_b32_e32 v35, 0xffff0000, v26
	v_lshlrev_b32_e32 v26, 16, v27
	v_and_b32_e32 v27, 0xffff0000, v27
	v_pk_mul_f32 v[28:29], v[28:29], s[20:21] op_sel_hi:[1,0]
	v_pk_mul_f32 v[20:21], v[20:21], s[20:21] op_sel_hi:[1,0]
	v_pk_mul_f32 v[30:31], v[30:31], s[20:21] op_sel_hi:[1,0]
	v_pk_mul_f32 v[32:33], v[32:33], s[20:21] op_sel_hi:[1,0]
	v_pk_fma_f32 v[10:11], v[10:11], 0.5, v[22:23] op_sel_hi:[1,0,1]
	v_pk_mul_f32 v[24:25], v[24:25], s[20:21] op_sel_hi:[1,0]
	v_pk_mul_f32 v[34:35], v[34:35], s[20:21] op_sel_hi:[1,0]
	v_pk_mul_f32 v[26:27], v[26:27], s[20:21] op_sel_hi:[1,0]
	v_pk_fma_f32 v[14:15], v[14:15], 0.5, v[20:21] op_sel_hi:[1,0,1]
	v_pk_fma_f32 v[12:13], v[12:13], 0.5, v[28:29] op_sel_hi:[1,0,1]
	v_pk_fma_f32 v[8:9], v[8:9], 0.5, v[30:31] op_sel_hi:[1,0,1]
	v_pk_fma_f32 v[4:5], v[4:5], 0.5, v[32:33] op_sel_hi:[1,0,1]
	v_mul_f32_e32 v32, v10, v10
	v_pk_fma_f32 v[6:7], v[6:7], 0.5, v[24:25] op_sel_hi:[1,0,1]
	v_pk_fma_f32 v[20:21], v[2:3], 0.5, v[26:27] op_sel_hi:[1,0,1]
	v_pk_fma_f32 v[22:23], v[0:1], 0.5, v[34:35] op_sel_hi:[1,0,1]
	v_cvt_pk_bf16_f32 v228, v12, v13
	v_cvt_pk_bf16_f32 v229, v14, v15
	v_add_f32_e32 v2, v12, v13
	v_add_f32_e32 v24, v14, v15
	v_mul_f32_e32 v27, v12, v12
	v_mul_f32_e32 v13, v13, v13
	v_mul_f32_e32 v29, v14, v14
	v_mul_f32_e32 v15, v15, v15
	v_cvt_pk_bf16_f32 v230, v8, v9
	v_mul_f32_e32 v3, v8, v8
	v_mul_f32_e32 v25, v9, v9
	v_mov_b32_e32 v26, v8
	v_mov_b32_e32 v12, v9
	v_mov_b32_e32 v28, v10
	v_mov_b32_e32 v14, v11
	v_pk_fma_f32 v[8:9], v[10:11], v[10:11], v[32:33] op_sel_hi:[1,1,0]
	v_cvt_pk_bf16_f32 v231, v10, v11
	v_mul_f32_e32 v35, v4, v4
	v_mul_f32_e32 v37, v5, v5
	v_mul_f32_e32 v39, v6, v6
	v_mul_f32_e32 v41, v7, v7
	v_mov_b32_e32 v34, v4
	v_mov_b32_e32 v36, v5
	v_mov_b32_e32 v38, v6
	v_mov_b32_e32 v40, v7
	v_pk_add_f32 v[10:11], v[26:27], v[12:13]
	v_pk_add_f32 v[12:13], v[28:29], v[14:15]
	v_pk_add_f32 v[2:3], v[2:3], v[24:25]
	v_mov_b32_e32 v133, v9
	v_mul_f32_e32 v43, v22, v22
	v_mul_f32_e32 v45, v23, v23
	v_mul_f32_e32 v47, v20, v20
	v_mul_f32_e32 v49, v21, v21
	v_mov_b32_e32 v42, v22
	v_mov_b32_e32 v44, v23
	v_mov_b32_e32 v46, v20
	v_mov_b32_e32 v48, v21
	v_pk_add_f32 v[14:15], v[34:35], v[36:37]
	v_pk_add_f32 v[24:25], v[38:39], v[40:41]
	v_pk_add_f32 v[10:11], v[10:11], v[12:13]
	v_pk_add_f32 v[2:3], v[2:3], v[132:133]
	v_pk_add_f32 v[26:27], v[42:43], v[44:45]
	v_pk_add_f32 v[28:29], v[46:47], v[48:49]
	v_pk_add_f32 v[8:9], v[14:15], v[24:25]
	v_pk_add_f32 v[2:3], v[10:11], v[2:3]
	v_pk_add_f32 v[12:13], v[26:27], v[28:29]
	v_pk_add_f32 v[2:3], v[2:3], v[8:9]
	s_nop 1
	v_permlane16_swap_b32_e32 v228, v230
	v_permlane16_swap_b32_e32 v229, v231
	v_lshl_add_u64 v[236:237], v[18:19], 0, v[238:239]
	global_store_dwordx4 v[236:237], v[228:231], off
	v_pk_add_f32 v[2:3], v[2:3], v[12:13]
	ds_bpermute_b32 v8, v156, v2
	ds_bpermute_b32 v9, v156, v3
	v_cvt_pk_bf16_f32 v232, v4, v5
	v_cvt_pk_bf16_f32 v233, v6, v7
	v_cvt_pk_bf16_f32 v234, v22, v23
	s_waitcnt lgkmcnt(0)
	v_pk_add_f32 v[0:1], v[2:3], v[8:9]
	ds_bpermute_b32 v2, v116, v0
	ds_bpermute_b32 v3, v116, v1
	v_cvt_pk_bf16_f32 v235, v20, v21
	s_nop 1
	v_permlane16_swap_b32_e32 v232, v234
	v_permlane16_swap_b32_e32 v233, v235
	global_store_dwordx4 v[236:237], v[232:235], off offset:256
	s_and_saveexec_b64 s[26:27], s[6:7]
	s_cbranch_execz .LBB0_287
	s_waitcnt lgkmcnt(0)
	v_pk_add_f32 v[0:1], v[0:1], v[2:3]
	v_and_b32_e32 v2, 0xff, v16
	v_bfe_u32 v3, v208, 6, 2
	v_lshlrev_b32_e32 v2, 5, v2
	v_lshl_add_u32 v2, v3, 3, v2
	v_add_u32_e32 v2, 0x20800, v2
	ds_write_b64 v2, v[0:1]
.LBB0_287:
	s_or_b64 exec, exec, s[26:27]
	s_waitcnt lgkmcnt(0)
	s_barrier
	v_lshlrev_b32_e32 v232, 4, v208
	v_add_u32_e32 v232, 0x20800, v232
	ds_read_b128 v[228:231], v232
	v_readfirstlane_b32 s98, v16
	s_andn2_b32 s98, s98, 0xff
	v_lshrrev_b32_e32 v233, 1, v208
	v_add_u32_e32 v233, s98, v233
	v_lshlrev_b32_e32 v233, 7, v233
	v_and_b32_e32 v234, 1, v208
	v_lshl_add_u32 v233, v234, 4, v233
	s_lshl_b32 s99, s24, 2
	s_and_b32 s99, s99, 0xffffffe0
	v_add_u32_e32 v233, s99, v233
	s_waitcnt lgkmcnt(0)
	global_store_dwordx4 v233, v[228:231], s[14:15]
	s_and_b64 vcc, exec, s[8:9]
	s_mov_b64 s[8:9], -1
	s_cbranch_vccnz .LBB0_256
	s_andn2_b64 vcc, exec, s[12:13]
	s_cbranch_vccnz .LBB0_255
	s_barrier
	s_branch .LBB0_255

; #define LAS __attribute__((address_space(3)))
; #define GASP __attribute__((address_space(1)))
;     __device__ __forceinline__ void operator()(Acc& acc, const Unit& u, int wr, int wc, int fr, int fq, LAS unsigned char* lds) const {
;     ...
;         const LAS f32x2* SL = (const LAS f32x2*)(lds + SL_OFF);
;         f32x4 gg[2][2], bb[2][2];
;         if (STp) {
; #pragma unroll
;             for (int bj = 0; bj < 2; ++bj)
; #pragma unroll
;                 for (int n = 0; n < 2; ++n) { gg[bj][n] = *(const GASP f32x4*)(gam + col0 + bj * HALF + n * 16); bb[bj][n] = *(const GASP f32x4*)(bet + col0 + bj * HALF + n * 16); }
;         }
; #pragma unroll
;         for (int ai = 0; ai < 2; ++ai)
; #pragma unroll
;             for (int m = 0; m < 4; ++m) {
;                 const int rl = ai * HALF + wr * 64 + m * 16 + fr, row = u.pm * BM + rl;
;                 const float* rp = (row < split) ? res0 + (size_t)row * D : res1 + (size_t)(row - split) * D;
;                 float* op = out + (size_t)row * D;
;                 f32x2 st = (f32x2){0.f, 1.f}; if (STp) st = SL[rl];
;                 float s = 0.f, q = 0.f;
; #pragma unroll
;                 for (int bj = 0; bj < 2; ++bj)
; #pragma unroll
;                     for (int n = 0; n < 2; ++n) { const int c = col0 + bj * HALF + n * 16; f32x4 r;
;                         if (resb) { const u32x2 w = *(const GASP u32x2*)(resb + (size_t)row * D + c);
;                             r = (f32x4){__uint_as_float(w.x << 16), __uint_as_float(w.x & 0xffff0000u), __uint_as_float(w.y << 16), __uint_as_float(w.y & 0xffff0000u)}; }
;                         else r = *(const GASP f32x4*)(rp + c);
;                         if (STp) r = (r - st[0]) * st[1] * gg[bj][n] + bb[bj][n];
;                         const f32x4 o = r * ALPHA + acc[ai][bj][m][n] * scale;
.LBB0_1044:
	s_or_b64 exec, exec, s[60:61]
	v_add_u32_e32 v176, s37, v180
	v_ashrrev_i32_e32 v64, 31, v176
	v_cmp_gt_i32_e32 vcc, s73, v176
	v_lshl_or_b32 v174, s50, 8, v182
	v_ashrrev_i32_e32 v175, 31, v174
	v_cndmask_b32_e32 v177, 0, v64, vcc
	v_lshlrev_b64 v[64:65], 11, v[176:177]
	v_lshl_add_u64 v[64:65], s[42:43], 0, v[64:65]
	s_waitcnt lgkmcnt(0)
	s_barrier
	v_lshl_add_u64 v[178:179], v[174:175], 1, v[64:65]
	global_load_dwordx2 v[204:205], v[178:179], off
	global_load_dwordx2 v[206:207], v[178:179], off offset:32
	global_load_dwordx2 v[210:211], v[178:179], off offset:256
	v_lshlrev_b64 v[64:65], 2, v[174:175]
	v_lshl_add_u64 v[92:93], s[18:19], 0, v[64:65]
	v_lshl_add_u64 v[88:89], s[16:17], 0, v[64:65]
	global_load_dwordx4 v[64:67], v[92:93], off
	global_load_dwordx4 v[76:79], v[88:89], off
	global_load_dwordx4 v[68:71], v[88:89], off offset:64
	global_load_dwordx4 v[80:83], v[92:93], off offset:64
	global_load_dwordx4 v[72:75], v[88:89], off offset:512
	global_load_dwordx4 v[84:87], v[92:93], off offset:512
	global_load_dwordx2 v[212:213], v[178:179], off offset:288
	ds_read_b64 v[214:215], v184
	global_load_dwordx4 v[88:91], v[88:89], off offset:576
	s_nop 0
	global_load_dwordx4 v[92:95], v[92:93], off offset:576
	s_lshl_b32 s14, s50, 3
	s_or_b32 s14, s14, s69
	s_ashr_i32 s15, s14, 31
	s_waitcnt vmcnt(0)
	v_lshlrev_b32_e32 v165, 16, v204
	v_and_b32_e32 v204, 0xffff0000, v204
	v_lshlrev_b32_e32 v216, 16, v205
	v_and_b32_e32 v217, 0xffff0000, v205
	v_lshlrev_b32_e32 v222, 16, v206
	v_and_b32_e32 v223, 0xffff0000, v206
	v_lshlrev_b32_e32 v224, 16, v207
	v_and_b32_e32 v225, 0xffff0000, v207
	v_lshlrev_b32_e32 v226, 16, v210
	v_and_b32_e32 v227, 0xffff0000, v210
	v_lshlrev_b32_e32 v228, 16, v211
	v_and_b32_e32 v229, 0xffff0000, v211
	s_waitcnt lgkmcnt(0)
	v_sub_f32_e32 v205, v204, v214
	v_sub_f32_e32 v204, v165, v214
	v_sub_f32_e32 v207, v217, v214
	v_sub_f32_e32 v206, v216, v214
	v_sub_f32_e32 v211, v225, v214
	v_sub_f32_e32 v210, v224, v214
	v_sub_f32_e32 v217, v223, v214
	v_sub_f32_e32 v216, v222, v214
	v_pk_mul_f32 v[206:207], v[214:215], v[206:207] op_sel:[1,0]
	v_pk_mul_f32 v[204:205], v[214:215], v[204:205] op_sel:[1,0]
	v_pk_mul_f32 v[216:217], v[214:215], v[216:217] op_sel:[1,0]
	v_pk_mul_f32 v[210:211], v[214:215], v[210:211] op_sel:[1,0]
	v_sub_f32_e32 v219, v229, v214
	v_sub_f32_e32 v218, v228, v214
	v_sub_f32_e32 v221, v227, v214
	v_sub_f32_e32 v220, v226, v214
	v_pk_fma_f32 v[204:205], v[76:77], v[204:205], v[64:65]
	v_pk_fma_f32 v[206:207], v[78:79], v[206:207], v[66:67]
	v_pk_fma_f32 v[210:211], v[70:71], v[210:211], v[82:83]
	v_pk_fma_f32 v[216:217], v[68:69], v[216:217], v[80:81]
	v_pk_mul_f32 v[220:221], v[214:215], v[220:221] op_sel:[1,0]
	v_pk_mul_f32 v[218:219], v[214:215], v[218:219] op_sel:[1,0]
	v_pk_fma_f32 v[158:159], v[206:207], s[34:35], v[158:159] op_sel_hi:[1,0,1]
	v_pk_fma_f32 v[156:157], v[204:205], s[34:35], v[156:157] op_sel_hi:[1,0,1]
	v_cndmask_b32_e64 v205, v217, v223, s[10:11]
	v_cndmask_b32_e64 v204, v216, v222, s[10:11]
	v_cndmask_b32_e64 v207, v211, v225, s[10:11]
	v_cndmask_b32_e64 v206, v210, v224, s[10:11]
	v_pk_fma_f32 v[218:219], v[74:75], v[218:219], v[86:87]
	v_pk_fma_f32 v[220:221], v[72:73], v[220:221], v[84:85]
	v_pk_fma_f32 v[154:155], v[206:207], s[34:35], v[154:155] op_sel_hi:[1,0,1]
	v_pk_fma_f32 v[152:153], v[204:205], s[34:35], v[152:153] op_sel_hi:[1,0,1]
	v_cndmask_b32_e64 v210, v220, v226, s[10:11]
	v_cndmask_b32_e64 v217, v219, v229, s[10:11]
	v_cvt_pk_bf16_f32 v236, v156, v157
	v_add_f32_e32 v222, v156, v157
	v_mul_f32_e32 v219, v156, v156
	v_mul_f32_e32 v157, v157, v157
	v_cvt_pk_bf16_f32 v238, v152, v153
	v_cvt_pk_bf16_f32 v239, v154, v155
	v_mul_f32_e32 v156, v154, v154
	v_pk_fma_f32 v[204:205], v[154:155], v[154:155], v[156:157] op_sel_hi:[1,1,0]
	v_cndmask_b32_e64 v211, v221, v227, s[10:11]
	v_lshlrev_b32_e32 v165, 16, v213
	v_and_b32_e32 v204, 0xffff0000, v213
	v_cvt_pk_bf16_f32 v237, v158, v159
	v_add_f32_e32 v224, v158, v159
	v_mul_f32_e32 v227, v158, v158
	v_pk_fma_f32 v[206:207], v[210:211], s[34:35], v[148:149] op_sel_hi:[1,0,1]
	v_lshlrev_b32_e32 v156, 16, v212
	v_and_b32_e32 v158, 0xffff0000, v212
	v_sub_f32_e32 v149, v204, v214
	v_sub_f32_e32 v148, v165, v214
	v_sub_f32_e32 v213, v158, v214
	v_sub_f32_e32 v212, v156, v214
	v_pk_mul_f32 v[148:149], v[214:215], v[148:149] op_sel:[1,0]
	v_pk_mul_f32 v[212:213], v[214:215], v[212:213] op_sel:[1,0]
	v_pk_fma_f32 v[148:149], v[90:91], v[148:149], v[94:95]
	v_pk_fma_f32 v[212:213], v[88:89], v[212:213], v[92:93]
	v_cndmask_b32_e64 v149, v149, v204, s[10:11]
	v_cndmask_b32_e64 v148, v148, v165, s[10:11]
	v_mul_f32_e32 v159, v159, v159
	v_cndmask_b32_e64 v216, v218, v228, s[10:11]
	v_cndmask_b32_e64 v213, v213, v158, s[10:11]
	v_cndmask_b32_e64 v212, v212, v156, s[10:11]
	v_pk_fma_f32 v[214:215], v[148:149], s[34:35], v[146:147] op_sel_hi:[1,0,1]
	v_and_b32_e32 v146, 64, v203
	v_mov_b32_e32 v218, v152
	v_mov_b32_e32 v156, v153
	v_mov_b32_e32 v226, v154
	v_mov_b32_e32 v158, v155
	v_mul_f32_e32 v223, v152, v152
	v_mul_f32_e32 v225, v153, v153
	v_pk_fma_f32 v[212:213], v[212:213], s[34:35], v[144:145] op_sel_hi:[1,0,1]
	v_xor_b32_e32 v144, 16, v203
	v_add_u32_e32 v149, 64, v146
	v_pk_add_f32 v[152:153], v[218:219], v[156:157]
	v_pk_add_f32 v[154:155], v[226:227], v[158:159]
	v_pk_fma_f32 v[150:151], v[216:217], s[34:35], v[150:151] op_sel_hi:[1,0,1]
	v_cmp_lt_i32_e32 vcc, v144, v149
	v_pk_add_f32 v[152:153], v[152:153], v[154:155]
	v_pk_add_f32 v[154:155], v[222:223], v[224:225]
	v_mov_b32_e32 v165, v205
	s_nop 1
	v_permlane16_swap_b32_e32 v236, v238
	v_permlane16_swap_b32_e32 v237, v239
; #define GASP __attribute__((address_space(1)))
;     __device__ __forceinline__ void operator()(Acc& acc, const Unit& u, int wr, int wc, int fr, int fq, LAS unsigned char* lds) const {
;     ...
;                 const int rl = ai * HALF + wr * 64 + m * 16 + fr, row = u.pm * BM + rl;
;                 const float* rp = (row < split) ? res0 + (size_t)row * D : res1 + (size_t)(row - split) * D;
;                 float* op = out + (size_t)row * D;
;                 f32x2 st = (f32x2){0.f, 1.f}; if (STp) st = SL[rl];
;                 float s = 0.f, q = 0.f;
; #pragma unroll
;                 for (int bj = 0; bj < 2; ++bj)
; #pragma unroll
;                     for (int n = 0; n < 2; ++n) { const int c = col0 + bj * HALF + n * 16; f32x4 r;
;                         if (resb) { const u32x2 w = *(const GASP u32x2*)(resb + (size_t)row * D + c);
;                             r = (f32x4){__uint_as_float(w.x << 16), __uint_as_float(w.x & 0xffff0000u), __uint_as_float(w.y << 16), __uint_as_float(w.y & 0xffff0000u)}; }
;                         else r = *(const GASP f32x4*)(rp + c);
;                         if (STp) r = (r - st[0]) * st[1] * gg[bj][n] + bb[bj][n];
;                         const f32x4 o = r * ALPHA + acc[ai][bj][m][n] * scale;
;                         if (out) *(GASP f32x4*)(op + c) = o;
;                         if (ob) { u32x2 w; w.x = pk2(o[0], o[1]); w.y = pk2(o[2], o[3]); *(GASP u32x2*)(ob + (size_t)row * D + c) = w; }
;                         s += (o[0] + o[1]) + (o[2] + o[3]); q += (o[0] * o[0] + o[1] * o[1]) + (o[2] * o[2] + o[3] * o[3]); }
;                 if (STn) { s += __shfl_xor(s, 16); s += __shfl_xor(s, 32); q += __shfl_xor(q, 16); q += __shfl_xor(q, 32);
;                     if (fq == 0) *(GASP f32x2*)(STn + (size_t)row * 32 + (u.pn * 4 + wc) * 2) = (f32x2){s, q}; }
	v_lshl_add_u64 v[244:245], v[178:179], 0, v[246:247]
	global_store_dwordx4 v[244:245], v[236:239], off
	v_mul_f32_e32 v217, v206, v206
	v_mul_f32_e32 v221, v207, v207
	v_mul_f32_e32 v229, v150, v150
	v_mul_f32_e32 v231, v151, v151
	v_cndmask_b32_e32 v144, v203, v144, vcc
	v_pk_add_f32 v[154:155], v[154:155], v[164:165]
	v_mov_b32_e32 v216, v206
	v_mov_b32_e32 v220, v207
	v_mov_b32_e32 v228, v150
	v_mov_b32_e32 v230, v151
	v_cvt_pk_bf16_f32 v241, v150, v151
	v_mul_f32_e32 v145, v212, v212
	v_mul_f32_e32 v147, v213, v213
	v_mul_f32_e32 v233, v214, v214
	v_mul_f32_e32 v235, v215, v215
	v_lshlrev_b32_e32 v148, 2, v144
	v_pk_add_f32 v[152:153], v[152:153], v[154:155]
	v_pk_add_f32 v[154:155], v[216:217], v[220:221]
	v_pk_add_f32 v[150:151], v[228:229], v[230:231]
	v_mov_b32_e32 v144, v212
	v_mov_b32_e32 v146, v213
	v_mov_b32_e32 v232, v214
	v_mov_b32_e32 v234, v215
	v_pk_add_f32 v[150:151], v[154:155], v[150:151]
	v_pk_add_f32 v[144:145], v[144:145], v[146:147]
	v_pk_add_f32 v[146:147], v[232:233], v[234:235]
	v_pk_add_f32 v[150:151], v[152:153], v[150:151]
	v_pk_add_f32 v[144:145], v[144:145], v[146:147]
	v_cvt_pk_bf16_f32 v240, v206, v207
	v_pk_add_f32 v[144:145], v[150:151], v[144:145]
	ds_bpermute_b32 v146, v148, v144
	ds_bpermute_b32 v147, v148, v145
	v_xor_b32_e32 v150, 32, v203
	v_cmp_lt_i32_e32 vcc, v150, v149
	v_cvt_pk_bf16_f32 v243, v214, v215
	v_cndmask_b32_e32 v149, v203, v150, vcc
	v_lshlrev_b32_e32 v149, 2, v149
	s_waitcnt lgkmcnt(0)
	v_pk_add_f32 v[144:145], v[144:145], v[146:147]
	ds_bpermute_b32 v146, v149, v144
	ds_bpermute_b32 v147, v149, v145
	v_cvt_pk_bf16_f32 v242, v212, v213
	s_nop 1
	v_permlane16_swap_b32_e32 v240, v242
	v_permlane16_swap_b32_e32 v241, v243
	global_store_dwordx4 v[244:245], v[240:243], off offset:256
	s_and_saveexec_b64 s[50:51], s[8:9]
	s_cbranch_execz .LBB0_1046
	s_waitcnt lgkmcnt(0)
	v_pk_add_f32 v[144:145], v[144:145], v[146:147]
	v_and_b32_e32 v146, 0xff, v176
	v_bfe_u32 v147, v208, 6, 2
	v_lshlrev_b32_e32 v146, 5, v146
	v_lshl_add_u32 v146, v147, 3, v146
	v_add_u32_e32 v146, 0x20800, v146
	ds_write_b64 v146, v[144:145]
.LBB0_1046:
	s_or_b64 exec, exec, s[50:51]
	v_add_u32_e32 v144, s37, v185
	v_ashrrev_i32_e32 v145, 31, v144
	v_cmp_gt_i32_e32 vcc, s73, v144
	s_nop 1
	v_cndmask_b32_e32 v145, 0, v145, vcc
	s_waitcnt lgkmcnt(0)
	v_lshlrev_b64 v[146:147], 11, v[144:145]
	v_lshl_add_u64 v[146:147], s[42:43], 0, v[146:147]
	v_lshl_add_u64 v[146:147], v[174:175], 1, v[146:147]
	global_load_dwordx2 v[150:151], v[146:147], off
	global_load_dwordx2 v[152:153], v[146:147], off offset:32
	global_load_dwordx2 v[154:155], v[146:147], off offset:256
	global_load_dwordx2 v[156:157], v[146:147], off offset:288
	ds_read_b64 v[158:159], v186
	s_waitcnt vmcnt(3)
	v_lshlrev_b32_e32 v176, 16, v151
	v_and_b32_e32 v177, 0xffff0000, v151
	s_waitcnt vmcnt(2)
	v_lshlrev_b32_e32 v212, 16, v153
	v_and_b32_e32 v213, 0xffff0000, v153
	v_lshlrev_b32_e32 v165, 16, v150
	v_and_b32_e32 v150, 0xffff0000, v150
	v_lshlrev_b32_e32 v210, 16, v152
	v_and_b32_e32 v211, 0xffff0000, v152
	s_waitcnt vmcnt(1)
	v_lshlrev_b32_e32 v214, 16, v154
	v_and_b32_e32 v215, 0xffff0000, v154
	v_lshlrev_b32_e32 v216, 16, v155
	v_and_b32_e32 v217, 0xffff0000, v155
	s_waitcnt lgkmcnt(0)
	v_sub_f32_e32 v153, v177, v158
	v_sub_f32_e32 v152, v176, v158
	v_sub_f32_e32 v155, v213, v158
	v_sub_f32_e32 v154, v212, v158
	s_waitcnt vmcnt(0)
	v_lshlrev_b32_e32 v218, 16, v156
	v_and_b32_e32 v219, 0xffff0000, v156
	v_lshlrev_b32_e32 v220, 16, v157
	v_and_b32_e32 v221, 0xffff0000, v157
	v_sub_f32_e32 v151, v150, v158
	v_sub_f32_e32 v150, v165, v158
	v_sub_f32_e32 v157, v211, v158
	v_sub_f32_e32 v156, v210, v158
	v_pk_mul_f32 v[152:153], v[158:159], v[152:153] op_sel:[1,0]
	v_pk_mul_f32 v[154:155], v[158:159], v[154:155] op_sel:[1,0]
	v_sub_f32_e32 v177, v217, v158
	v_sub_f32_e32 v176, v216, v158
	v_sub_f32_e32 v179, v215, v158
	v_sub_f32_e32 v178, v214, v158
	v_sub_f32_e32 v207, v219, v158
	v_sub_f32_e32 v206, v218, v158
	v_pk_mul_f32 v[150:151], v[158:159], v[150:151] op_sel:[1,0]
	v_pk_mul_f32 v[156:157], v[158:159], v[156:157] op_sel:[1,0]
	v_pk_fma_f32 v[152:153], v[78:79], v[152:153], v[66:67]
	v_pk_fma_f32 v[154:155], v[70:71], v[154:155], v[82:83]
	v_sub_f32_e32 v205, v221, v158
	v_sub_f32_e32 v204, v220, v158
	v_pk_mul_f32 v[178:179], v[158:159], v[178:179] op_sel:[1,0]
	v_pk_mul_f32 v[176:177], v[158:159], v[176:177] op_sel:[1,0]
	v_pk_mul_f32 v[206:207], v[158:159], v[206:207] op_sel:[1,0]
	v_pk_fma_f32 v[150:151], v[76:77], v[150:151], v[64:65]
	v_pk_fma_f32 v[156:157], v[68:69], v[156:157], v[80:81]
	v_pk_fma_f32 v[142:143], v[152:153], s[34:35], v[142:143] op_sel_hi:[1,0,1]
	v_cndmask_b32_e64 v153, v155, v213, s[10:11]
	v_cndmask_b32_e64 v152, v154, v212, s[10:11]
	v_pk_mul_f32 v[158:159], v[158:159], v[204:205] op_sel:[1,0]
	v_pk_fma_f32 v[176:177], v[74:75], v[176:177], v[86:87]
	v_pk_fma_f32 v[178:179], v[72:73], v[178:179], v[84:85]
	v_pk_fma_f32 v[204:205], v[88:89], v[206:207], v[92:93]
	v_pk_fma_f32 v[140:141], v[150:151], s[34:35], v[140:141] op_sel_hi:[1,0,1]
	v_cndmask_b32_e64 v151, v157, v211, s[10:11]
	v_cndmask_b32_e64 v150, v156, v210, s[10:11]
	v_pk_fma_f32 v[138:139], v[152:153], s[34:35], v[138:139] op_sel_hi:[1,0,1]
	v_cndmask_b32_e64 v154, v178, v214, s[10:11]
	v_cndmask_b32_e64 v156, v176, v216, s[10:11]
	v_cndmask_b32_e64 v176, v204, v218, s[10:11]
	v_cvt_pk_bf16_f32 v236, v140, v141
	v_add_f32_e32 v204, v140, v141
	v_mul_f32_e32 v211, v140, v140
	v_mul_f32_e32 v141, v141, v141
	v_pk_fma_f32 v[136:137], v[150:151], s[34:35], v[136:137] op_sel_hi:[1,0,1]
	v_mul_f32_e32 v140, v138, v138
	v_cndmask_b32_e64 v155, v179, v215, s[10:11]
; #define GASP __attribute__((address_space(1)))
;     __device__ __forceinline__ void operator()(Acc& acc, const Unit& u, int wr, int wc, int fr, int fq, LAS unsigned char* lds) const {
;     ...
;                 const int rl = ai * HALF + wr * 64 + m * 16 + fr, row = u.pm * BM + rl;
;                 const float* rp = (row < split) ? res0 + (size_t)row * D : res1 + (size_t)(row - split) * D;
;                 float* op = out + (size_t)row * D;
;                 f32x2 st = (f32x2){0.f, 1.f}; if (STp) st = SL[rl];
;                 float s = 0.f, q = 0.f;
; #pragma unroll
;                 for (int bj = 0; bj < 2; ++bj)
; #pragma unroll
;                     for (int n = 0; n < 2; ++n) { const int c = col0 + bj * HALF + n * 16; f32x4 r;
;                         if (resb) { const u32x2 w = *(const GASP u32x2*)(resb + (size_t)row * D + c);
;                             r = (f32x4){__uint_as_float(w.x << 16), __uint_as_float(w.x & 0xffff0000u), __uint_as_float(w.y << 16), __uint_as_float(w.y & 0xffff0000u)}; }
;                         else r = *(const GASP f32x4*)(rp + c);
;                         if (STp) r = (r - st[0]) * st[1] * gg[bj][n] + bb[bj][n];
;                         const f32x4 o = r * ALPHA + acc[ai][bj][m][n] * scale;
;                         if (out) *(GASP f32x4*)(op + c) = o;
;                         if (ob) { u32x2 w; w.x = pk2(o[0], o[1]); w.y = pk2(o[2], o[3]); *(GASP u32x2*)(ob + (size_t)row * D + c) = w; }
;                         s += (o[0] + o[1]) + (o[2] + o[3]); q += (o[0] * o[0] + o[1] * o[1]) + (o[2] * o[2] + o[3] * o[3]); }
;                 if (STn) { s += __shfl_xor(s, 16); s += __shfl_xor(s, 32); q += __shfl_xor(q, 16); q += __shfl_xor(q, 32);
;                     if (fq == 0) *(GASP f32x2*)(STn + (size_t)row * 32 + (u.pn * 4 + wc) * 2) = (f32x2){s, q}; }
	v_cvt_pk_bf16_f32 v237, v142, v143
	v_add_f32_e32 v206, v142, v143
	v_mul_f32_e32 v213, v142, v142
	v_mul_f32_e32 v143, v143, v143
	v_pk_fma_f32 v[214:215], v[138:139], v[138:139], v[140:141] op_sel_hi:[1,1,0]
	v_mov_b32_e32 v210, v136
	v_mov_b32_e32 v140, v137
	v_mov_b32_e32 v212, v138
	v_mov_b32_e32 v142, v139
	v_pk_fma_f32 v[158:159], v[90:91], v[158:159], v[94:95]
	v_cndmask_b32_e64 v157, v177, v217, s[10:11]
	v_cndmask_b32_e64 v177, v205, v219, s[10:11]
	v_cvt_pk_bf16_f32 v238, v136, v137
	v_mul_f32_e32 v205, v136, v136
	v_mul_f32_e32 v207, v137, v137
	v_pk_add_f32 v[136:137], v[210:211], v[140:141]
	v_pk_add_f32 v[140:141], v[212:213], v[142:143]
	v_pk_fma_f32 v[134:135], v[156:157], s[34:35], v[134:135] op_sel_hi:[1,0,1]
	v_pk_fma_f32 v[132:133], v[154:155], s[34:35], v[132:133] op_sel_hi:[1,0,1]
	v_cndmask_b32_e64 v159, v159, v221, s[10:11]
	v_cndmask_b32_e64 v158, v158, v220, s[10:11]
	v_pk_add_f32 v[136:137], v[136:137], v[140:141]
	v_pk_add_f32 v[140:141], v[204:205], v[206:207]
	v_mov_b32_e32 v165, v215
	v_mul_f32_e32 v153, v132, v132
	v_mul_f32_e32 v155, v133, v133
	v_mul_f32_e32 v157, v134, v134
	v_mul_f32_e32 v179, v135, v135
	v_pk_fma_f32 v[158:159], v[158:159], s[34:35], v[130:131] op_sel_hi:[1,0,1]
	v_pk_fma_f32 v[176:177], v[176:177], s[34:35], v[128:129] op_sel_hi:[1,0,1]
	v_pk_add_f32 v[140:141], v[140:141], v[164:165]
	v_mov_b32_e32 v152, v132
	v_mov_b32_e32 v154, v133
	v_mov_b32_e32 v156, v134
	v_mov_b32_e32 v178, v135
	v_mul_f32_e32 v129, v176, v176
	v_mul_f32_e32 v131, v177, v177
	v_mul_f32_e32 v217, v158, v158
	v_mul_f32_e32 v219, v159, v159
	v_pk_add_f32 v[136:137], v[136:137], v[140:141]
	v_pk_add_f32 v[140:141], v[152:153], v[154:155]
	v_pk_add_f32 v[142:143], v[156:157], v[178:179]
	v_mov_b32_e32 v128, v176
	v_mov_b32_e32 v130, v177
	v_mov_b32_e32 v216, v158
	v_mov_b32_e32 v218, v159
	v_pk_add_f32 v[140:141], v[140:141], v[142:143]
	v_pk_add_f32 v[128:129], v[128:129], v[130:131]
	v_pk_add_f32 v[130:131], v[216:217], v[218:219]
	v_pk_add_f32 v[136:137], v[136:137], v[140:141]
	v_pk_add_f32 v[128:129], v[128:129], v[130:131]
	v_cvt_pk_bf16_f32 v240, v132, v133
	v_pk_add_f32 v[128:129], v[136:137], v[128:129]
	ds_bpermute_b32 v130, v148, v128
	ds_bpermute_b32 v131, v148, v129
	v_cvt_pk_bf16_f32 v241, v134, v135
	v_cvt_pk_bf16_f32 v239, v138, v139
	v_cvt_pk_bf16_f32 v242, v176, v177
	s_waitcnt lgkmcnt(0)
	v_pk_add_f32 v[128:129], v[128:129], v[130:131]
	ds_bpermute_b32 v130, v149, v128
	ds_bpermute_b32 v131, v149, v129
	v_cvt_pk_bf16_f32 v243, v158, v159
	s_nop 1
	v_permlane16_swap_b32_e32 v236, v238
	v_permlane16_swap_b32_e32 v237, v239
	v_lshl_add_u64 v[244:245], v[146:147], 0, v[246:247]
	global_store_dwordx4 v[244:245], v[236:239], off
	s_nop 1
	v_permlane16_swap_b32_e32 v240, v242
	v_permlane16_swap_b32_e32 v241, v243
	global_store_dwordx4 v[244:245], v[240:243], off offset:256
	s_and_saveexec_b64 s[50:51], s[8:9]
	s_cbranch_execz .LBB0_1048
	s_waitcnt lgkmcnt(0)
	v_pk_add_f32 v[128:129], v[128:129], v[130:131]
	v_and_b32_e32 v130, 0xff, v144
	v_bfe_u32 v131, v208, 6, 2
	v_lshlrev_b32_e32 v130, 5, v130
	v_lshl_add_u32 v130, v131, 3, v130
	v_add_u32_e32 v130, 0x20800, v130
	ds_write_b64 v130, v[128:129]
.LBB0_1048:
	s_or_b64 exec, exec, s[50:51]
	v_add_u32_e32 v128, s37, v187
	v_ashrrev_i32_e32 v129, 31, v128
	v_cmp_gt_i32_e32 vcc, s73, v128
	s_nop 1
	v_cndmask_b32_e32 v129, 0, v129, vcc
	s_waitcnt lgkmcnt(0)
	v_lshlrev_b64 v[130:131], 11, v[128:129]
	v_lshl_add_u64 v[130:131], s[42:43], 0, v[130:131]
	v_lshl_add_u64 v[130:131], v[174:175], 1, v[130:131]
	global_load_dwordx2 v[132:133], v[130:131], off
	global_load_dwordx2 v[134:135], v[130:131], off offset:32
	global_load_dwordx2 v[136:137], v[130:131], off offset:256
	global_load_dwordx2 v[138:139], v[130:131], off offset:288
	ds_read_b64 v[140:141], v188
	s_waitcnt vmcnt(3)
	v_lshlrev_b32_e32 v143, 16, v133
	v_and_b32_e32 v144, 0xffff0000, v133
	s_waitcnt vmcnt(2)
	v_lshlrev_b32_e32 v154, 16, v135
	v_and_b32_e32 v155, 0xffff0000, v135
	v_lshlrev_b32_e32 v142, 16, v132
	v_and_b32_e32 v132, 0xffff0000, v132
	v_lshlrev_b32_e32 v152, 16, v134
	v_and_b32_e32 v153, 0xffff0000, v134
	s_waitcnt vmcnt(1)
	v_lshlrev_b32_e32 v156, 16, v136
	v_and_b32_e32 v157, 0xffff0000, v136
	v_lshlrev_b32_e32 v158, 16, v137
	v_and_b32_e32 v159, 0xffff0000, v137
	s_waitcnt lgkmcnt(0)
	v_sub_f32_e32 v135, v144, v140
	v_sub_f32_e32 v134, v143, v140
	v_sub_f32_e32 v137, v155, v140
	v_sub_f32_e32 v136, v154, v140
	s_waitcnt vmcnt(0)
; #define GASP __attribute__((address_space(1)))
;     __device__ __forceinline__ void operator()(Acc& acc, const Unit& u, int wr, int wc, int fr, int fq, LAS unsigned char* lds) const {
;     ...
;                 const int rl = ai * HALF + wr * 64 + m * 16 + fr, row = u.pm * BM + rl;
;                 const float* rp = (row < split) ? res0 + (size_t)row * D : res1 + (size_t)(row - split) * D;
;                 float* op = out + (size_t)row * D;
;                 f32x2 st = (f32x2){0.f, 1.f}; if (STp) st = SL[rl];
;                 float s = 0.f, q = 0.f;
; #pragma unroll
;                 for (int bj = 0; bj < 2; ++bj)
; #pragma unroll
;                     for (int n = 0; n < 2; ++n) { const int c = col0 + bj * HALF + n * 16; f32x4 r;
;                         if (resb) { const u32x2 w = *(const GASP u32x2*)(resb + (size_t)row * D + c);
;                             r = (f32x4){__uint_as_float(w.x << 16), __uint_as_float(w.x & 0xffff0000u), __uint_as_float(w.y << 16), __uint_as_float(w.y & 0xffff0000u)}; }
;                         else r = *(const GASP f32x4*)(rp + c);
;                         if (STp) r = (r - st[0]) * st[1] * gg[bj][n] + bb[bj][n];
;                         const f32x4 o = r * ALPHA + acc[ai][bj][m][n] * scale;
;                         if (out) *(GASP f32x4*)(op + c) = o;
;                         if (ob) { u32x2 w; w.x = pk2(o[0], o[1]); w.y = pk2(o[2], o[3]); *(GASP u32x2*)(ob + (size_t)row * D + c) = w; }
;                         s += (o[0] + o[1]) + (o[2] + o[3]); q += (o[0] * o[0] + o[1] * o[1]) + (o[2] * o[2] + o[3] * o[3]); }
;                 if (STn) { s += __shfl_xor(s, 16); s += __shfl_xor(s, 32); q += __shfl_xor(q, 16); q += __shfl_xor(q, 32);
;                     if (fq == 0) *(GASP f32x2*)(STn + (size_t)row * 32 + (u.pn * 4 + wc) * 2) = (f32x2){s, q}; }
	v_lshlrev_b32_e32 v165, 16, v138
	v_and_b32_e32 v176, 0xffff0000, v138
	v_lshlrev_b32_e32 v177, 16, v139
	v_and_b32_e32 v178, 0xffff0000, v139
	v_sub_f32_e32 v133, v132, v140
	v_sub_f32_e32 v132, v142, v140
	v_sub_f32_e32 v139, v153, v140
	v_sub_f32_e32 v138, v152, v140
	v_pk_mul_f32 v[134:135], v[140:141], v[134:135] op_sel:[1,0]
	v_pk_mul_f32 v[136:137], v[140:141], v[136:137] op_sel:[1,0]
	v_sub_f32_e32 v143, v159, v140
	v_sub_f32_e32 v142, v158, v140
	v_sub_f32_e32 v145, v157, v140
	v_sub_f32_e32 v144, v156, v140
	v_sub_f32_e32 v151, v176, v140
	v_sub_f32_e32 v150, v165, v140
	v_pk_mul_f32 v[132:133], v[140:141], v[132:133] op_sel:[1,0]
	v_pk_mul_f32 v[138:139], v[140:141], v[138:139] op_sel:[1,0]
	v_pk_fma_f32 v[134:135], v[78:79], v[134:135], v[66:67]
	v_pk_fma_f32 v[136:137], v[70:71], v[136:137], v[82:83]
	v_sub_f32_e32 v147, v178, v140
	v_sub_f32_e32 v146, v177, v140
	v_pk_mul_f32 v[144:145], v[140:141], v[144:145] op_sel:[1,0]
	v_pk_mul_f32 v[142:143], v[140:141], v[142:143] op_sel:[1,0]
	v_pk_mul_f32 v[150:151], v[140:141], v[150:151] op_sel:[1,0]
	v_pk_fma_f32 v[132:133], v[76:77], v[132:133], v[64:65]
	v_pk_fma_f32 v[138:139], v[68:69], v[138:139], v[80:81]
	v_pk_fma_f32 v[126:127], v[134:135], s[34:35], v[126:127] op_sel_hi:[1,0,1]
	v_cndmask_b32_e64 v135, v137, v155, s[10:11]
	v_cndmask_b32_e64 v134, v136, v154, s[10:11]
	v_pk_mul_f32 v[140:141], v[140:141], v[146:147] op_sel:[1,0]
	v_pk_fma_f32 v[142:143], v[74:75], v[142:143], v[86:87]
	v_pk_fma_f32 v[144:145], v[72:73], v[144:145], v[84:85]
	v_pk_fma_f32 v[146:147], v[88:89], v[150:151], v[92:93]
	v_pk_fma_f32 v[124:125], v[132:133], s[34:35], v[124:125] op_sel_hi:[1,0,1]
	v_cndmask_b32_e64 v133, v139, v153, s[10:11]
	v_cndmask_b32_e64 v132, v138, v152, s[10:11]
	v_pk_fma_f32 v[122:123], v[134:135], s[34:35], v[122:123] op_sel_hi:[1,0,1]
	v_cndmask_b32_e64 v136, v144, v156, s[10:11]
	v_cndmask_b32_e64 v138, v142, v158, s[10:11]
	v_cndmask_b32_e64 v142, v146, v165, s[10:11]
	v_cvt_pk_bf16_f32 v236, v124, v125
	v_add_f32_e32 v146, v124, v125
	v_mul_f32_e32 v153, v124, v124
	v_mul_f32_e32 v125, v125, v125
	v_pk_fma_f32 v[120:121], v[132:133], s[34:35], v[120:121] op_sel_hi:[1,0,1]
	v_mul_f32_e32 v124, v122, v122
	v_cndmask_b32_e64 v137, v145, v157, s[10:11]
	v_cvt_pk_bf16_f32 v237, v126, v127
	v_add_f32_e32 v150, v126, v127
	v_mul_f32_e32 v155, v126, v126
	v_mul_f32_e32 v127, v127, v127
	v_pk_fma_f32 v[156:157], v[122:123], v[122:123], v[124:125] op_sel_hi:[1,1,0]
	v_mov_b32_e32 v152, v120
	v_mov_b32_e32 v124, v121
	v_mov_b32_e32 v154, v122
	v_mov_b32_e32 v126, v123
	v_pk_fma_f32 v[140:141], v[90:91], v[140:141], v[94:95]
	v_cndmask_b32_e64 v139, v143, v159, s[10:11]
	v_cndmask_b32_e64 v143, v147, v176, s[10:11]
	v_cvt_pk_bf16_f32 v238, v120, v121
	v_mul_f32_e32 v147, v120, v120
	v_mul_f32_e32 v151, v121, v121
	v_pk_add_f32 v[120:121], v[152:153], v[124:125]
	v_pk_add_f32 v[124:125], v[154:155], v[126:127]
	v_pk_fma_f32 v[118:119], v[138:139], s[34:35], v[118:119] op_sel_hi:[1,0,1]
	v_pk_fma_f32 v[116:117], v[136:137], s[34:35], v[116:117] op_sel_hi:[1,0,1]
	v_cndmask_b32_e64 v141, v141, v178, s[10:11]
	v_cndmask_b32_e64 v140, v140, v177, s[10:11]
	v_pk_add_f32 v[120:121], v[120:121], v[124:125]
	v_pk_add_f32 v[124:125], v[146:147], v[150:151]
	v_mov_b32_e32 v165, v157
	v_mul_f32_e32 v135, v116, v116
	v_mul_f32_e32 v137, v117, v117
	v_mul_f32_e32 v139, v118, v118
	v_mul_f32_e32 v145, v119, v119
	v_pk_fma_f32 v[140:141], v[140:141], s[34:35], v[114:115] op_sel_hi:[1,0,1]
	v_pk_fma_f32 v[142:143], v[142:143], s[34:35], v[112:113] op_sel_hi:[1,0,1]
	v_pk_add_f32 v[124:125], v[124:125], v[164:165]
	v_mov_b32_e32 v134, v116
	v_mov_b32_e32 v136, v117
	v_mov_b32_e32 v138, v118
	v_mov_b32_e32 v144, v119
	v_mul_f32_e32 v113, v142, v142
	v_mul_f32_e32 v115, v143, v143
	v_mul_f32_e32 v159, v140, v140
	v_mul_f32_e32 v177, v141, v141
	v_pk_add_f32 v[120:121], v[120:121], v[124:125]
	v_pk_add_f32 v[124:125], v[134:135], v[136:137]
	v_pk_add_f32 v[126:127], v[138:139], v[144:145]
	v_mov_b32_e32 v112, v142
	v_mov_b32_e32 v114, v143
	v_mov_b32_e32 v158, v140
	v_mov_b32_e32 v176, v141
	v_pk_add_f32 v[124:125], v[124:125], v[126:127]
	v_pk_add_f32 v[112:113], v[112:113], v[114:115]
	v_pk_add_f32 v[114:115], v[158:159], v[176:177]
	v_pk_add_f32 v[120:121], v[120:121], v[124:125]
	v_pk_add_f32 v[112:113], v[112:113], v[114:115]
	v_cvt_pk_bf16_f32 v240, v116, v117
	v_pk_add_f32 v[112:113], v[120:121], v[112:113]
	ds_bpermute_b32 v114, v148, v112
	ds_bpermute_b32 v115, v148, v113
	v_cvt_pk_bf16_f32 v241, v118, v119
	v_cvt_pk_bf16_f32 v239, v122, v123
	v_cvt_pk_bf16_f32 v242, v142, v143
	s_waitcnt lgkmcnt(0)
	v_pk_add_f32 v[112:113], v[112:113], v[114:115]
	ds_bpermute_b32 v114, v149, v112
	ds_bpermute_b32 v115, v149, v113
	v_cvt_pk_bf16_f32 v243, v140, v141
	s_nop 1
	v_permlane16_swap_b32_e32 v236, v238
	v_permlane16_swap_b32_e32 v237, v239
	v_lshl_add_u64 v[244:245], v[130:131], 0, v[246:247]
	global_store_dwordx4 v[244:245], v[236:239], off
	s_nop 1
	v_permlane16_swap_b32_e32 v240, v242
	v_permlane16_swap_b32_e32 v241, v243
	global_store_dwordx4 v[244:245], v[240:243], off offset:256
	s_and_saveexec_b64 s[50:51], s[8:9]
	s_cbranch_execz .LBB0_1050
	s_waitcnt lgkmcnt(0)
	v_pk_add_f32 v[112:113], v[112:113], v[114:115]
	v_and_b32_e32 v114, 0xff, v128
	v_bfe_u32 v115, v208, 6, 2
	v_lshlrev_b32_e32 v114, 5, v114
	v_lshl_add_u32 v114, v115, 3, v114
	v_add_u32_e32 v114, 0x20800, v114
	ds_write_b64 v114, v[112:113]
; #define GASP __attribute__((address_space(1)))
;     __device__ __forceinline__ void operator()(Acc& acc, const Unit& u, int wr, int wc, int fr, int fq, LAS unsigned char* lds) const {
;     ...
;                 const int rl = ai * HALF + wr * 64 + m * 16 + fr, row = u.pm * BM + rl;
;                 const float* rp = (row < split) ? res0 + (size_t)row * D : res1 + (size_t)(row - split) * D;
;                 float* op = out + (size_t)row * D;
;                 f32x2 st = (f32x2){0.f, 1.f}; if (STp) st = SL[rl];
;                 float s = 0.f, q = 0.f;
; #pragma unroll
;                 for (int bj = 0; bj < 2; ++bj)
; #pragma unroll
;                     for (int n = 0; n < 2; ++n) { const int c = col0 + bj * HALF + n * 16; f32x4 r;
;                         if (resb) { const u32x2 w = *(const GASP u32x2*)(resb + (size_t)row * D + c);
;                             r = (f32x4){__uint_as_float(w.x << 16), __uint_as_float(w.x & 0xffff0000u), __uint_as_float(w.y << 16), __uint_as_float(w.y & 0xffff0000u)}; }
;                         else r = *(const GASP f32x4*)(rp + c);
;                         if (STp) r = (r - st[0]) * st[1] * gg[bj][n] + bb[bj][n];
;                         const f32x4 o = r * ALPHA + acc[ai][bj][m][n] * scale;
;                         if (out) *(GASP f32x4*)(op + c) = o;
;                         if (ob) { u32x2 w; w.x = pk2(o[0], o[1]); w.y = pk2(o[2], o[3]); *(GASP u32x2*)(ob + (size_t)row * D + c) = w; }
;                         s += (o[0] + o[1]) + (o[2] + o[3]); q += (o[0] * o[0] + o[1] * o[1]) + (o[2] * o[2] + o[3] * o[3]); }
;                 if (STn) { s += __shfl_xor(s, 16); s += __shfl_xor(s, 32); q += __shfl_xor(q, 16); q += __shfl_xor(q, 32);
;                     if (fq == 0) *(GASP f32x2*)(STn + (size_t)row * 32 + (u.pn * 4 + wc) * 2) = (f32x2){s, q}; }
.LBB0_1050:
	s_or_b64 exec, exec, s[50:51]
	v_add_u32_e32 v112, s37, v189
	v_ashrrev_i32_e32 v113, 31, v112
	v_cmp_gt_i32_e32 vcc, s73, v112
	s_nop 1
	v_cndmask_b32_e32 v113, 0, v113, vcc
	s_waitcnt lgkmcnt(0)
	v_lshlrev_b64 v[114:115], 11, v[112:113]
	v_lshl_add_u64 v[114:115], s[42:43], 0, v[114:115]
	v_lshl_add_u64 v[114:115], v[174:175], 1, v[114:115]
	global_load_dwordx2 v[116:117], v[114:115], off
	global_load_dwordx2 v[118:119], v[114:115], off offset:32
	global_load_dwordx2 v[120:121], v[114:115], off offset:256
	global_load_dwordx2 v[122:123], v[114:115], off offset:288
	ds_read_b64 v[124:125], v190
	s_waitcnt vmcnt(3)
	v_lshlrev_b32_e32 v127, 16, v117
	v_and_b32_e32 v128, 0xffff0000, v117
	s_waitcnt vmcnt(2)
	v_lshlrev_b32_e32 v136, 16, v119
	v_and_b32_e32 v137, 0xffff0000, v119
	v_lshlrev_b32_e32 v126, 16, v116
	v_and_b32_e32 v116, 0xffff0000, v116
	v_lshlrev_b32_e32 v134, 16, v118
	v_and_b32_e32 v135, 0xffff0000, v118
	s_waitcnt vmcnt(1)
	v_lshlrev_b32_e32 v138, 16, v120
	v_and_b32_e32 v139, 0xffff0000, v120
	v_lshlrev_b32_e32 v140, 16, v121
	v_and_b32_e32 v141, 0xffff0000, v121
	s_waitcnt lgkmcnt(0)
	v_sub_f32_e32 v119, v128, v124
	v_sub_f32_e32 v118, v127, v124
	v_sub_f32_e32 v121, v137, v124
	v_sub_f32_e32 v120, v136, v124
	s_waitcnt vmcnt(0)
	v_lshlrev_b32_e32 v142, 16, v122
	v_and_b32_e32 v143, 0xffff0000, v122
	v_lshlrev_b32_e32 v144, 16, v123
	v_and_b32_e32 v145, 0xffff0000, v123
	v_sub_f32_e32 v117, v116, v124
	v_sub_f32_e32 v116, v126, v124
	v_sub_f32_e32 v123, v135, v124
	v_sub_f32_e32 v122, v134, v124
	v_pk_mul_f32 v[118:119], v[124:125], v[118:119] op_sel:[1,0]
	v_pk_mul_f32 v[120:121], v[124:125], v[120:121] op_sel:[1,0]
	v_sub_f32_e32 v127, v141, v124
	v_sub_f32_e32 v126, v140, v124
	v_sub_f32_e32 v129, v139, v124
	v_sub_f32_e32 v128, v138, v124
	v_sub_f32_e32 v133, v143, v124
	v_sub_f32_e32 v132, v142, v124
	v_pk_mul_f32 v[116:117], v[124:125], v[116:117] op_sel:[1,0]
	v_pk_mul_f32 v[122:123], v[124:125], v[122:123] op_sel:[1,0]
	v_pk_fma_f32 v[118:119], v[78:79], v[118:119], v[66:67]
	v_pk_fma_f32 v[120:121], v[70:71], v[120:121], v[82:83]
	v_sub_f32_e32 v131, v145, v124
	v_sub_f32_e32 v130, v144, v124
	v_pk_mul_f32 v[128:129], v[124:125], v[128:129] op_sel:[1,0]
	v_pk_mul_f32 v[126:127], v[124:125], v[126:127] op_sel:[1,0]
	v_pk_mul_f32 v[132:133], v[124:125], v[132:133] op_sel:[1,0]
	v_pk_fma_f32 v[116:117], v[76:77], v[116:117], v[64:65]
	v_pk_fma_f32 v[122:123], v[68:69], v[122:123], v[80:81]
	v_pk_fma_f32 v[110:111], v[118:119], s[34:35], v[110:111] op_sel_hi:[1,0,1]
	v_cndmask_b32_e64 v119, v121, v137, s[10:11]
	v_cndmask_b32_e64 v118, v120, v136, s[10:11]
	v_pk_mul_f32 v[124:125], v[124:125], v[130:131] op_sel:[1,0]
	v_pk_fma_f32 v[126:127], v[74:75], v[126:127], v[86:87]
	v_pk_fma_f32 v[128:129], v[72:73], v[128:129], v[84:85]
	v_pk_fma_f32 v[130:131], v[88:89], v[132:133], v[92:93]
	v_pk_fma_f32 v[108:109], v[116:117], s[34:35], v[108:109] op_sel_hi:[1,0,1]
	v_cndmask_b32_e64 v117, v123, v135, s[10:11]
	v_cndmask_b32_e64 v116, v122, v134, s[10:11]
	v_pk_fma_f32 v[106:107], v[118:119], s[34:35], v[106:107] op_sel_hi:[1,0,1]
	v_cndmask_b32_e64 v120, v128, v138, s[10:11]
	v_cndmask_b32_e64 v122, v126, v140, s[10:11]
	v_cndmask_b32_e64 v126, v130, v142, s[10:11]
	v_cvt_pk_bf16_f32 v236, v108, v109
	v_add_f32_e32 v130, v108, v109
	v_mul_f32_e32 v135, v108, v108
	v_mul_f32_e32 v109, v109, v109
	v_pk_fma_f32 v[104:105], v[116:117], s[34:35], v[104:105] op_sel_hi:[1,0,1]
	v_mul_f32_e32 v108, v106, v106
	v_cndmask_b32_e64 v121, v129, v139, s[10:11]
	v_cvt_pk_bf16_f32 v237, v110, v111
	v_add_f32_e32 v132, v110, v111
	v_mul_f32_e32 v137, v110, v110
	v_mul_f32_e32 v111, v111, v111
	v_pk_fma_f32 v[138:139], v[106:107], v[106:107], v[108:109] op_sel_hi:[1,1,0]
	v_mov_b32_e32 v134, v104
	v_mov_b32_e32 v108, v105
	v_mov_b32_e32 v136, v106
	v_mov_b32_e32 v110, v107
	v_pk_fma_f32 v[124:125], v[90:91], v[124:125], v[94:95]
	v_cndmask_b32_e64 v123, v127, v141, s[10:11]
	v_cndmask_b32_e64 v127, v131, v143, s[10:11]
	v_cvt_pk_bf16_f32 v238, v104, v105
	v_mul_f32_e32 v131, v104, v104
	v_mul_f32_e32 v133, v105, v105
	v_pk_add_f32 v[104:105], v[134:135], v[108:109]
	v_pk_add_f32 v[108:109], v[136:137], v[110:111]
	v_pk_fma_f32 v[102:103], v[122:123], s[34:35], v[102:103] op_sel_hi:[1,0,1]
	v_pk_fma_f32 v[100:101], v[120:121], s[34:35], v[100:101] op_sel_hi:[1,0,1]
	v_cndmask_b32_e64 v125, v125, v145, s[10:11]
	v_cndmask_b32_e64 v124, v124, v144, s[10:11]
	v_pk_add_f32 v[104:105], v[104:105], v[108:109]
	v_pk_add_f32 v[108:109], v[130:131], v[132:133]
	v_mov_b32_e32 v165, v139
	v_mul_f32_e32 v119, v100, v100
	v_mul_f32_e32 v121, v101, v101
	v_mul_f32_e32 v123, v102, v102
	v_mul_f32_e32 v129, v103, v103
	v_pk_fma_f32 v[124:125], v[124:125], s[34:35], v[98:99] op_sel_hi:[1,0,1]
	v_pk_fma_f32 v[126:127], v[126:127], s[34:35], v[96:97] op_sel_hi:[1,0,1]
	v_pk_add_f32 v[108:109], v[108:109], v[164:165]
	v_mov_b32_e32 v118, v100
	v_mov_b32_e32 v120, v101
	v_mov_b32_e32 v122, v102
	v_mov_b32_e32 v128, v103
	v_mul_f32_e32 v97, v126, v126
	v_mul_f32_e32 v99, v127, v127
	v_mul_f32_e32 v141, v124, v124
	v_mul_f32_e32 v143, v125, v125
	v_pk_add_f32 v[104:105], v[104:105], v[108:109]
	v_pk_add_f32 v[108:109], v[118:119], v[120:121]
	v_pk_add_f32 v[110:111], v[122:123], v[128:129]
	v_mov_b32_e32 v96, v126
	v_mov_b32_e32 v98, v127
	v_mov_b32_e32 v140, v124
	v_mov_b32_e32 v142, v125
	v_pk_add_f32 v[108:109], v[108:109], v[110:111]
	v_pk_add_f32 v[96:97], v[96:97], v[98:99]
	v_pk_add_f32 v[98:99], v[140:141], v[142:143]
	v_pk_add_f32 v[104:105], v[104:105], v[108:109]
	v_pk_add_f32 v[96:97], v[96:97], v[98:99]
	v_cvt_pk_bf16_f32 v240, v100, v101
	v_pk_add_f32 v[96:97], v[104:105], v[96:97]
	ds_bpermute_b32 v98, v148, v96
	ds_bpermute_b32 v99, v148, v97
	v_cvt_pk_bf16_f32 v241, v102, v103
	v_cvt_pk_bf16_f32 v239, v106, v107
	v_cvt_pk_bf16_f32 v242, v126, v127
	s_waitcnt lgkmcnt(0)
	v_pk_add_f32 v[96:97], v[96:97], v[98:99]
	ds_bpermute_b32 v98, v149, v96
	ds_bpermute_b32 v99, v149, v97
	v_cvt_pk_bf16_f32 v243, v124, v125
	s_nop 1
	v_permlane16_swap_b32_e32 v236, v238
	v_permlane16_swap_b32_e32 v237, v239
	v_lshl_add_u64 v[244:245], v[114:115], 0, v[246:247]
	global_store_dwordx4 v[244:245], v[236:239], off
	s_nop 1
	v_permlane16_swap_b32_e32 v240, v242
	v_permlane16_swap_b32_e32 v241, v243
	global_store_dwordx4 v[244:245], v[240:243], off offset:256
	s_and_saveexec_b64 s[50:51], s[8:9]
	s_cbranch_execz .LBB0_1052
	s_waitcnt lgkmcnt(0)
	v_pk_add_f32 v[96:97], v[96:97], v[98:99]
	v_and_b32_e32 v98, 0xff, v112
	v_bfe_u32 v99, v208, 6, 2
	v_lshlrev_b32_e32 v98, 5, v98
	v_lshl_add_u32 v98, v99, 3, v98
	v_add_u32_e32 v98, 0x20800, v98
	ds_write_b64 v98, v[96:97]
; #define GASP __attribute__((address_space(1)))
;     __device__ __forceinline__ void operator()(Acc& acc, const Unit& u, int wr, int wc, int fr, int fq, LAS unsigned char* lds) const {
;     ...
;                 const int rl = ai * HALF + wr * 64 + m * 16 + fr, row = u.pm * BM + rl;
;                 const float* rp = (row < split) ? res0 + (size_t)row * D : res1 + (size_t)(row - split) * D;
;                 float* op = out + (size_t)row * D;
;                 f32x2 st = (f32x2){0.f, 1.f}; if (STp) st = SL[rl];
;                 float s = 0.f, q = 0.f;
; #pragma unroll
;                 for (int bj = 0; bj < 2; ++bj)
; #pragma unroll
;                     for (int n = 0; n < 2; ++n) { const int c = col0 + bj * HALF + n * 16; f32x4 r;
;                         if (resb) { const u32x2 w = *(const GASP u32x2*)(resb + (size_t)row * D + c);
;                             r = (f32x4){__uint_as_float(w.x << 16), __uint_as_float(w.x & 0xffff0000u), __uint_as_float(w.y << 16), __uint_as_float(w.y & 0xffff0000u)}; }
;                         else r = *(const GASP f32x4*)(rp + c);
;                         if (STp) r = (r - st[0]) * st[1] * gg[bj][n] + bb[bj][n];
;                         const f32x4 o = r * ALPHA + acc[ai][bj][m][n] * scale;
;                         if (out) *(GASP f32x4*)(op + c) = o;
;                         if (ob) { u32x2 w; w.x = pk2(o[0], o[1]); w.y = pk2(o[2], o[3]); *(GASP u32x2*)(ob + (size_t)row * D + c) = w; }
;                         s += (o[0] + o[1]) + (o[2] + o[3]); q += (o[0] * o[0] + o[1] * o[1]) + (o[2] * o[2] + o[3] * o[3]); }
;                 if (STn) { s += __shfl_xor(s, 16); s += __shfl_xor(s, 32); q += __shfl_xor(q, 16); q += __shfl_xor(q, 32);
;                     if (fq == 0) *(GASP f32x2*)(STn + (size_t)row * 32 + (u.pn * 4 + wc) * 2) = (f32x2){s, q}; }
.LBB0_1052:
	s_or_b64 exec, exec, s[50:51]
	v_add_u32_e32 v96, s37, v191
	v_ashrrev_i32_e32 v97, 31, v96
	v_cmp_gt_i32_e32 vcc, s73, v96
	s_nop 1
	v_cndmask_b32_e32 v97, 0, v97, vcc
	s_waitcnt lgkmcnt(0)
	v_lshlrev_b64 v[98:99], 11, v[96:97]
	v_lshl_add_u64 v[98:99], s[42:43], 0, v[98:99]
	v_lshl_add_u64 v[98:99], v[174:175], 1, v[98:99]
	global_load_dwordx2 v[100:101], v[98:99], off
	global_load_dwordx2 v[102:103], v[98:99], off offset:32
	global_load_dwordx2 v[104:105], v[98:99], off offset:256
	global_load_dwordx2 v[106:107], v[98:99], off offset:288
	ds_read_b64 v[108:109], v192
	s_waitcnt vmcnt(3)
	v_lshlrev_b32_e32 v111, 16, v101
	v_and_b32_e32 v112, 0xffff0000, v101
	s_waitcnt vmcnt(2)
	v_lshlrev_b32_e32 v120, 16, v103
	v_and_b32_e32 v121, 0xffff0000, v103
	v_lshlrev_b32_e32 v110, 16, v100
	v_and_b32_e32 v100, 0xffff0000, v100
	v_lshlrev_b32_e32 v118, 16, v102
	v_and_b32_e32 v119, 0xffff0000, v102
	s_waitcnt vmcnt(1)
	v_lshlrev_b32_e32 v122, 16, v104
	v_and_b32_e32 v123, 0xffff0000, v104
	v_lshlrev_b32_e32 v124, 16, v105
	v_and_b32_e32 v125, 0xffff0000, v105
	s_waitcnt lgkmcnt(0)
	v_sub_f32_e32 v103, v112, v108
	v_sub_f32_e32 v102, v111, v108
	v_sub_f32_e32 v105, v121, v108
	v_sub_f32_e32 v104, v120, v108
	s_waitcnt vmcnt(0)
	v_lshlrev_b32_e32 v126, 16, v106
	v_and_b32_e32 v127, 0xffff0000, v106
	v_lshlrev_b32_e32 v128, 16, v107
	v_and_b32_e32 v129, 0xffff0000, v107
	v_sub_f32_e32 v101, v100, v108
	v_sub_f32_e32 v100, v110, v108
	v_sub_f32_e32 v107, v119, v108
	v_sub_f32_e32 v106, v118, v108
	v_pk_mul_f32 v[102:103], v[108:109], v[102:103] op_sel:[1,0]
	v_pk_mul_f32 v[104:105], v[108:109], v[104:105] op_sel:[1,0]
	v_sub_f32_e32 v111, v125, v108
	v_sub_f32_e32 v110, v124, v108
	v_sub_f32_e32 v113, v123, v108
	v_sub_f32_e32 v112, v122, v108
	v_sub_f32_e32 v117, v127, v108
	v_sub_f32_e32 v116, v126, v108
	v_pk_mul_f32 v[100:101], v[108:109], v[100:101] op_sel:[1,0]
	v_pk_mul_f32 v[106:107], v[108:109], v[106:107] op_sel:[1,0]
	v_pk_fma_f32 v[102:103], v[78:79], v[102:103], v[66:67]
	v_pk_fma_f32 v[104:105], v[70:71], v[104:105], v[82:83]
	v_sub_f32_e32 v115, v129, v108
	v_sub_f32_e32 v114, v128, v108
	v_pk_mul_f32 v[112:113], v[108:109], v[112:113] op_sel:[1,0]
	v_pk_mul_f32 v[110:111], v[108:109], v[110:111] op_sel:[1,0]
	v_pk_mul_f32 v[116:117], v[108:109], v[116:117] op_sel:[1,0]
	v_pk_fma_f32 v[100:101], v[76:77], v[100:101], v[64:65]
	v_pk_fma_f32 v[106:107], v[68:69], v[106:107], v[80:81]
	v_pk_fma_f32 v[62:63], v[102:103], s[34:35], v[62:63] op_sel_hi:[1,0,1]
	v_cndmask_b32_e64 v103, v105, v121, s[10:11]
	v_cndmask_b32_e64 v102, v104, v120, s[10:11]
	v_pk_mul_f32 v[108:109], v[108:109], v[114:115] op_sel:[1,0]
	v_pk_fma_f32 v[110:111], v[74:75], v[110:111], v[86:87]
	v_pk_fma_f32 v[112:113], v[72:73], v[112:113], v[84:85]
	v_pk_fma_f32 v[114:115], v[88:89], v[116:117], v[92:93]
	v_pk_fma_f32 v[60:61], v[100:101], s[34:35], v[60:61] op_sel_hi:[1,0,1]
	v_cndmask_b32_e64 v101, v107, v119, s[10:11]
	v_cndmask_b32_e64 v100, v106, v118, s[10:11]
	v_pk_fma_f32 v[58:59], v[102:103], s[34:35], v[58:59] op_sel_hi:[1,0,1]
	v_cndmask_b32_e64 v104, v112, v122, s[10:11]
	v_cndmask_b32_e64 v106, v110, v124, s[10:11]
	v_cndmask_b32_e64 v110, v114, v126, s[10:11]
	v_cvt_pk_bf16_f32 v236, v60, v61
	v_add_f32_e32 v114, v60, v61
	v_mul_f32_e32 v119, v60, v60
	v_mul_f32_e32 v61, v61, v61
	v_pk_fma_f32 v[56:57], v[100:101], s[34:35], v[56:57] op_sel_hi:[1,0,1]
	v_mul_f32_e32 v60, v58, v58
	v_cndmask_b32_e64 v105, v113, v123, s[10:11]
	v_cvt_pk_bf16_f32 v237, v62, v63
	v_add_f32_e32 v116, v62, v63
	v_mul_f32_e32 v121, v62, v62
	v_mul_f32_e32 v63, v63, v63
	v_pk_fma_f32 v[122:123], v[58:59], v[58:59], v[60:61] op_sel_hi:[1,1,0]
	v_mov_b32_e32 v118, v56
	v_mov_b32_e32 v60, v57
	v_mov_b32_e32 v120, v58
	v_mov_b32_e32 v62, v59
	v_pk_fma_f32 v[108:109], v[90:91], v[108:109], v[94:95]
	v_cndmask_b32_e64 v107, v111, v125, s[10:11]
	v_cndmask_b32_e64 v111, v115, v127, s[10:11]
	v_cvt_pk_bf16_f32 v238, v56, v57
	v_mul_f32_e32 v115, v56, v56
	v_mul_f32_e32 v117, v57, v57
	v_pk_add_f32 v[56:57], v[118:119], v[60:61]
	v_pk_add_f32 v[60:61], v[120:121], v[62:63]
	v_pk_fma_f32 v[54:55], v[106:107], s[34:35], v[54:55] op_sel_hi:[1,0,1]
	v_pk_fma_f32 v[52:53], v[104:105], s[34:35], v[52:53] op_sel_hi:[1,0,1]
	v_cndmask_b32_e64 v109, v109, v129, s[10:11]
	v_cndmask_b32_e64 v108, v108, v128, s[10:11]
	v_pk_add_f32 v[56:57], v[56:57], v[60:61]
	v_pk_add_f32 v[60:61], v[114:115], v[116:117]
	v_mov_b32_e32 v165, v123
	v_mul_f32_e32 v103, v52, v52
	v_mul_f32_e32 v105, v53, v53
	v_mul_f32_e32 v107, v54, v54
	v_mul_f32_e32 v113, v55, v55
	v_pk_fma_f32 v[108:109], v[108:109], s[34:35], v[50:51] op_sel_hi:[1,0,1]
	v_pk_fma_f32 v[110:111], v[110:111], s[34:35], v[48:49] op_sel_hi:[1,0,1]
	v_pk_add_f32 v[60:61], v[60:61], v[164:165]
	v_mov_b32_e32 v102, v52
	v_mov_b32_e32 v104, v53
	v_mov_b32_e32 v106, v54
	v_mov_b32_e32 v112, v55
	v_mul_f32_e32 v49, v110, v110
	v_mul_f32_e32 v51, v111, v111
	v_mul_f32_e32 v125, v108, v108
	v_mul_f32_e32 v127, v109, v109
	v_pk_add_f32 v[56:57], v[56:57], v[60:61]
	v_pk_add_f32 v[60:61], v[102:103], v[104:105]
	v_pk_add_f32 v[62:63], v[106:107], v[112:113]
	v_mov_b32_e32 v48, v110
	v_mov_b32_e32 v50, v111
	v_mov_b32_e32 v124, v108
	v_mov_b32_e32 v126, v109
	v_pk_add_f32 v[60:61], v[60:61], v[62:63]
	v_pk_add_f32 v[48:49], v[48:49], v[50:51]
	v_pk_add_f32 v[50:51], v[124:125], v[126:127]
	v_pk_add_f32 v[56:57], v[56:57], v[60:61]
	v_pk_add_f32 v[48:49], v[48:49], v[50:51]
	v_cvt_pk_bf16_f32 v240, v52, v53
	v_pk_add_f32 v[48:49], v[56:57], v[48:49]
	ds_bpermute_b32 v50, v148, v48
	ds_bpermute_b32 v51, v148, v49
	v_cvt_pk_bf16_f32 v241, v54, v55
	v_cvt_pk_bf16_f32 v239, v58, v59
	v_cvt_pk_bf16_f32 v242, v110, v111
	s_waitcnt lgkmcnt(0)
	v_pk_add_f32 v[48:49], v[48:49], v[50:51]
	ds_bpermute_b32 v50, v149, v48
	ds_bpermute_b32 v51, v149, v49
	v_cvt_pk_bf16_f32 v243, v108, v109
	s_nop 1
	v_permlane16_swap_b32_e32 v236, v238
	v_permlane16_swap_b32_e32 v237, v239
	v_lshl_add_u64 v[244:245], v[98:99], 0, v[246:247]
	global_store_dwordx4 v[244:245], v[236:239], off
	s_nop 1
	v_permlane16_swap_b32_e32 v240, v242
	v_permlane16_swap_b32_e32 v241, v243
	global_store_dwordx4 v[244:245], v[240:243], off offset:256
	s_and_saveexec_b64 s[50:51], s[8:9]
	s_cbranch_execz .LBB0_1054
	s_waitcnt lgkmcnt(0)
	v_pk_add_f32 v[48:49], v[48:49], v[50:51]
	v_and_b32_e32 v50, 0xff, v96
	v_bfe_u32 v51, v208, 6, 2
	v_lshlrev_b32_e32 v50, 5, v50
	v_lshl_add_u32 v50, v51, 3, v50
	v_add_u32_e32 v50, 0x20800, v50
	ds_write_b64 v50, v[48:49]
; #define GASP __attribute__((address_space(1)))
;     __device__ __forceinline__ void operator()(Acc& acc, const Unit& u, int wr, int wc, int fr, int fq, LAS unsigned char* lds) const {
;     ...
;                 const int rl = ai * HALF + wr * 64 + m * 16 + fr, row = u.pm * BM + rl;
;                 const float* rp = (row < split) ? res0 + (size_t)row * D : res1 + (size_t)(row - split) * D;
;                 float* op = out + (size_t)row * D;
;                 f32x2 st = (f32x2){0.f, 1.f}; if (STp) st = SL[rl];
;                 float s = 0.f, q = 0.f;
; #pragma unroll
;                 for (int bj = 0; bj < 2; ++bj)
; #pragma unroll
;                     for (int n = 0; n < 2; ++n) { const int c = col0 + bj * HALF + n * 16; f32x4 r;
;                         if (resb) { const u32x2 w = *(const GASP u32x2*)(resb + (size_t)row * D + c);
;                             r = (f32x4){__uint_as_float(w.x << 16), __uint_as_float(w.x & 0xffff0000u), __uint_as_float(w.y << 16), __uint_as_float(w.y & 0xffff0000u)}; }
;                         else r = *(const GASP f32x4*)(rp + c);
;                         if (STp) r = (r - st[0]) * st[1] * gg[bj][n] + bb[bj][n];
;                         const f32x4 o = r * ALPHA + acc[ai][bj][m][n] * scale;
;                         if (out) *(GASP f32x4*)(op + c) = o;
;                         if (ob) { u32x2 w; w.x = pk2(o[0], o[1]); w.y = pk2(o[2], o[3]); *(GASP u32x2*)(ob + (size_t)row * D + c) = w; }
;                         s += (o[0] + o[1]) + (o[2] + o[3]); q += (o[0] * o[0] + o[1] * o[1]) + (o[2] * o[2] + o[3] * o[3]); }
;                 if (STn) { s += __shfl_xor(s, 16); s += __shfl_xor(s, 32); q += __shfl_xor(q, 16); q += __shfl_xor(q, 32);
;                     if (fq == 0) *(GASP f32x2*)(STn + (size_t)row * 32 + (u.pn * 4 + wc) * 2) = (f32x2){s, q}; }
.LBB0_1054:
	s_or_b64 exec, exec, s[50:51]
	v_add_u32_e32 v48, s37, v193
	v_ashrrev_i32_e32 v49, 31, v48
	v_cmp_gt_i32_e32 vcc, s73, v48
	s_nop 1
	v_cndmask_b32_e32 v49, 0, v49, vcc
	s_waitcnt lgkmcnt(0)
	v_lshlrev_b64 v[50:51], 11, v[48:49]
	v_lshl_add_u64 v[50:51], s[42:43], 0, v[50:51]
	v_lshl_add_u64 v[50:51], v[174:175], 1, v[50:51]
	global_load_dwordx2 v[52:53], v[50:51], off
	global_load_dwordx2 v[54:55], v[50:51], off offset:32
	global_load_dwordx2 v[56:57], v[50:51], off offset:256
	global_load_dwordx2 v[58:59], v[50:51], off offset:288
	ds_read_b64 v[60:61], v194
	s_waitcnt vmcnt(3)
	v_lshlrev_b32_e32 v63, 16, v53
	v_and_b32_e32 v96, 0xffff0000, v53
	s_waitcnt vmcnt(2)
	v_lshlrev_b32_e32 v104, 16, v55
	v_and_b32_e32 v105, 0xffff0000, v55
	v_lshlrev_b32_e32 v62, 16, v52
	v_and_b32_e32 v52, 0xffff0000, v52
	v_lshlrev_b32_e32 v102, 16, v54
	v_and_b32_e32 v103, 0xffff0000, v54
	s_waitcnt vmcnt(1)
	v_lshlrev_b32_e32 v106, 16, v56
	v_and_b32_e32 v107, 0xffff0000, v56
	v_lshlrev_b32_e32 v108, 16, v57
	v_and_b32_e32 v109, 0xffff0000, v57
	s_waitcnt lgkmcnt(0)
	v_sub_f32_e32 v55, v96, v60
	v_sub_f32_e32 v54, v63, v60
	v_sub_f32_e32 v57, v105, v60
	v_sub_f32_e32 v56, v104, v60
	s_waitcnt vmcnt(0)
	v_lshlrev_b32_e32 v110, 16, v58
	v_and_b32_e32 v111, 0xffff0000, v58
	v_lshlrev_b32_e32 v112, 16, v59
	v_and_b32_e32 v113, 0xffff0000, v59
	v_sub_f32_e32 v53, v52, v60
	v_sub_f32_e32 v52, v62, v60
	v_sub_f32_e32 v59, v103, v60
	v_sub_f32_e32 v58, v102, v60
	v_pk_mul_f32 v[54:55], v[60:61], v[54:55] op_sel:[1,0]
	v_pk_mul_f32 v[56:57], v[60:61], v[56:57] op_sel:[1,0]
	v_sub_f32_e32 v63, v109, v60
	v_sub_f32_e32 v62, v108, v60
	v_sub_f32_e32 v97, v107, v60
	v_sub_f32_e32 v96, v106, v60
	v_sub_f32_e32 v101, v111, v60
	v_sub_f32_e32 v100, v110, v60
	v_pk_mul_f32 v[52:53], v[60:61], v[52:53] op_sel:[1,0]
	v_pk_mul_f32 v[58:59], v[60:61], v[58:59] op_sel:[1,0]
	v_pk_fma_f32 v[54:55], v[78:79], v[54:55], v[66:67]
	v_pk_fma_f32 v[56:57], v[70:71], v[56:57], v[82:83]
	v_sub_f32_e32 v99, v113, v60
	v_sub_f32_e32 v98, v112, v60
	v_pk_mul_f32 v[96:97], v[60:61], v[96:97] op_sel:[1,0]
	v_pk_mul_f32 v[62:63], v[60:61], v[62:63] op_sel:[1,0]
	v_pk_mul_f32 v[100:101], v[60:61], v[100:101] op_sel:[1,0]
	v_pk_fma_f32 v[52:53], v[76:77], v[52:53], v[64:65]
	v_pk_fma_f32 v[58:59], v[68:69], v[58:59], v[80:81]
	v_pk_fma_f32 v[46:47], v[54:55], s[34:35], v[46:47] op_sel_hi:[1,0,1]
	v_cndmask_b32_e64 v55, v57, v105, s[10:11]
	v_cndmask_b32_e64 v54, v56, v104, s[10:11]
	v_pk_mul_f32 v[60:61], v[60:61], v[98:99] op_sel:[1,0]
	v_pk_fma_f32 v[62:63], v[74:75], v[62:63], v[86:87]
	v_pk_fma_f32 v[96:97], v[72:73], v[96:97], v[84:85]
	v_pk_fma_f32 v[98:99], v[88:89], v[100:101], v[92:93]
	v_pk_fma_f32 v[44:45], v[52:53], s[34:35], v[44:45] op_sel_hi:[1,0,1]
	v_cndmask_b32_e64 v53, v59, v103, s[10:11]
	v_cndmask_b32_e64 v52, v58, v102, s[10:11]
	v_pk_fma_f32 v[42:43], v[54:55], s[34:35], v[42:43] op_sel_hi:[1,0,1]
	v_cndmask_b32_e64 v56, v96, v106, s[10:11]
	v_cndmask_b32_e64 v58, v62, v108, s[10:11]
	v_cndmask_b32_e64 v62, v98, v110, s[10:11]
	v_cvt_pk_bf16_f32 v236, v44, v45
	v_add_f32_e32 v98, v44, v45
	v_mul_f32_e32 v103, v44, v44
	v_mul_f32_e32 v45, v45, v45
	v_pk_fma_f32 v[40:41], v[52:53], s[34:35], v[40:41] op_sel_hi:[1,0,1]
	v_mul_f32_e32 v44, v42, v42
	v_cndmask_b32_e64 v57, v97, v107, s[10:11]
	v_cvt_pk_bf16_f32 v237, v46, v47
	v_add_f32_e32 v100, v46, v47
	v_mul_f32_e32 v105, v46, v46
	v_mul_f32_e32 v47, v47, v47
	v_pk_fma_f32 v[106:107], v[42:43], v[42:43], v[44:45] op_sel_hi:[1,1,0]
	v_mov_b32_e32 v102, v40
	v_mov_b32_e32 v44, v41
	v_mov_b32_e32 v104, v42
	v_mov_b32_e32 v46, v43
	v_pk_fma_f32 v[60:61], v[90:91], v[60:61], v[94:95]
	v_cndmask_b32_e64 v59, v63, v109, s[10:11]
	v_cndmask_b32_e64 v63, v99, v111, s[10:11]
	v_cvt_pk_bf16_f32 v238, v40, v41
	v_mul_f32_e32 v99, v40, v40
	v_mul_f32_e32 v101, v41, v41
	v_pk_add_f32 v[40:41], v[102:103], v[44:45]
	v_pk_add_f32 v[44:45], v[104:105], v[46:47]
	v_pk_fma_f32 v[38:39], v[58:59], s[34:35], v[38:39] op_sel_hi:[1,0,1]
	v_pk_fma_f32 v[36:37], v[56:57], s[34:35], v[36:37] op_sel_hi:[1,0,1]
	v_cndmask_b32_e64 v61, v61, v113, s[10:11]
	v_cndmask_b32_e64 v60, v60, v112, s[10:11]
	v_pk_add_f32 v[40:41], v[40:41], v[44:45]
	v_pk_add_f32 v[44:45], v[98:99], v[100:101]
	v_mov_b32_e32 v165, v107
	v_mul_f32_e32 v55, v36, v36
	v_mul_f32_e32 v57, v37, v37
	v_mul_f32_e32 v59, v38, v38
	v_mul_f32_e32 v97, v39, v39
	v_pk_fma_f32 v[60:61], v[60:61], s[34:35], v[34:35] op_sel_hi:[1,0,1]
	v_pk_fma_f32 v[62:63], v[62:63], s[34:35], v[32:33] op_sel_hi:[1,0,1]
	v_pk_add_f32 v[44:45], v[44:45], v[164:165]
	v_mov_b32_e32 v54, v36
	v_mov_b32_e32 v56, v37
	v_mov_b32_e32 v58, v38
	v_mov_b32_e32 v96, v39
	v_mul_f32_e32 v33, v62, v62
	v_mul_f32_e32 v35, v63, v63
	v_mul_f32_e32 v109, v60, v60
	v_mul_f32_e32 v111, v61, v61
	v_pk_add_f32 v[40:41], v[40:41], v[44:45]
	v_pk_add_f32 v[44:45], v[54:55], v[56:57]
	v_pk_add_f32 v[46:47], v[58:59], v[96:97]
	v_mov_b32_e32 v32, v62
	v_mov_b32_e32 v34, v63
	v_mov_b32_e32 v108, v60
	v_mov_b32_e32 v110, v61
	v_pk_add_f32 v[44:45], v[44:45], v[46:47]
	v_pk_add_f32 v[32:33], v[32:33], v[34:35]
	v_pk_add_f32 v[34:35], v[108:109], v[110:111]
	v_pk_add_f32 v[40:41], v[40:41], v[44:45]
	v_pk_add_f32 v[32:33], v[32:33], v[34:35]
	v_cvt_pk_bf16_f32 v240, v36, v37
	v_pk_add_f32 v[32:33], v[40:41], v[32:33]
	ds_bpermute_b32 v34, v148, v32
	ds_bpermute_b32 v35, v148, v33
	v_cvt_pk_bf16_f32 v241, v38, v39
	v_cvt_pk_bf16_f32 v239, v42, v43
	v_cvt_pk_bf16_f32 v242, v62, v63
	s_waitcnt lgkmcnt(0)
	v_pk_add_f32 v[32:33], v[32:33], v[34:35]
	ds_bpermute_b32 v34, v149, v32
	ds_bpermute_b32 v35, v149, v33
	v_cvt_pk_bf16_f32 v243, v60, v61
	s_nop 1
	v_permlane16_swap_b32_e32 v236, v238
	v_permlane16_swap_b32_e32 v237, v239
	v_lshl_add_u64 v[244:245], v[50:51], 0, v[246:247]
	global_store_dwordx4 v[244:245], v[236:239], off
	s_nop 1
	v_permlane16_swap_b32_e32 v240, v242
	v_permlane16_swap_b32_e32 v241, v243
	global_store_dwordx4 v[244:245], v[240:243], off offset:256
	s_and_saveexec_b64 s[50:51], s[8:9]
	s_cbranch_execz .LBB0_1056
	s_waitcnt lgkmcnt(0)
	v_pk_add_f32 v[32:33], v[32:33], v[34:35]
	v_and_b32_e32 v34, 0xff, v48
	v_bfe_u32 v35, v208, 6, 2
	v_lshlrev_b32_e32 v34, 5, v34
	v_lshl_add_u32 v34, v35, 3, v34
	v_add_u32_e32 v34, 0x20800, v34
	ds_write_b64 v34, v[32:33]
; #define GASP __attribute__((address_space(1)))
;     __device__ __forceinline__ void operator()(Acc& acc, const Unit& u, int wr, int wc, int fr, int fq, LAS unsigned char* lds) const {
;     ...
;                 const int rl = ai * HALF + wr * 64 + m * 16 + fr, row = u.pm * BM + rl;
;                 const float* rp = (row < split) ? res0 + (size_t)row * D : res1 + (size_t)(row - split) * D;
;                 float* op = out + (size_t)row * D;
;                 f32x2 st = (f32x2){0.f, 1.f}; if (STp) st = SL[rl];
;                 float s = 0.f, q = 0.f;
; #pragma unroll
;                 for (int bj = 0; bj < 2; ++bj)
; #pragma unroll
;                     for (int n = 0; n < 2; ++n) { const int c = col0 + bj * HALF + n * 16; f32x4 r;
;                         if (resb) { const u32x2 w = *(const GASP u32x2*)(resb + (size_t)row * D + c);
;                             r = (f32x4){__uint_as_float(w.x << 16), __uint_as_float(w.x & 0xffff0000u), __uint_as_float(w.y << 16), __uint_as_float(w.y & 0xffff0000u)}; }
;                         else r = *(const GASP f32x4*)(rp + c);
;                         if (STp) r = (r - st[0]) * st[1] * gg[bj][n] + bb[bj][n];
;                         const f32x4 o = r * ALPHA + acc[ai][bj][m][n] * scale;
;                         if (out) *(GASP f32x4*)(op + c) = o;
;                         if (ob) { u32x2 w; w.x = pk2(o[0], o[1]); w.y = pk2(o[2], o[3]); *(GASP u32x2*)(ob + (size_t)row * D + c) = w; }
;                         s += (o[0] + o[1]) + (o[2] + o[3]); q += (o[0] * o[0] + o[1] * o[1]) + (o[2] * o[2] + o[3] * o[3]); }
;                 if (STn) { s += __shfl_xor(s, 16); s += __shfl_xor(s, 32); q += __shfl_xor(q, 16); q += __shfl_xor(q, 32);
;                     if (fq == 0) *(GASP f32x2*)(STn + (size_t)row * 32 + (u.pn * 4 + wc) * 2) = (f32x2){s, q}; }
.LBB0_1056:
	s_or_b64 exec, exec, s[50:51]
	v_add_u32_e32 v32, s37, v195
	v_ashrrev_i32_e32 v33, 31, v32
	v_cmp_gt_i32_e32 vcc, s73, v32
	s_nop 1
	v_cndmask_b32_e32 v33, 0, v33, vcc
	s_waitcnt lgkmcnt(0)
	v_lshlrev_b64 v[34:35], 11, v[32:33]
	v_lshl_add_u64 v[34:35], s[42:43], 0, v[34:35]
	v_lshl_add_u64 v[34:35], v[174:175], 1, v[34:35]
	global_load_dwordx2 v[36:37], v[34:35], off
	global_load_dwordx2 v[38:39], v[34:35], off offset:32
	global_load_dwordx2 v[40:41], v[34:35], off offset:256
	global_load_dwordx2 v[42:43], v[34:35], off offset:288
	ds_read_b64 v[44:45], v196
	s_waitcnt vmcnt(3)
	v_lshlrev_b32_e32 v47, 16, v37
	v_and_b32_e32 v48, 0xffff0000, v37
	s_waitcnt vmcnt(2)
	v_lshlrev_b32_e32 v56, 16, v39
	v_and_b32_e32 v57, 0xffff0000, v39
	v_lshlrev_b32_e32 v46, 16, v36
	v_and_b32_e32 v36, 0xffff0000, v36
	v_lshlrev_b32_e32 v54, 16, v38
	v_and_b32_e32 v55, 0xffff0000, v38
	s_waitcnt vmcnt(1)
	v_lshlrev_b32_e32 v58, 16, v40
	v_and_b32_e32 v59, 0xffff0000, v40
	v_lshlrev_b32_e32 v60, 16, v41
	v_and_b32_e32 v61, 0xffff0000, v41
	s_waitcnt lgkmcnt(0)
	v_sub_f32_e32 v39, v48, v44
	v_sub_f32_e32 v38, v47, v44
	v_sub_f32_e32 v41, v57, v44
	v_sub_f32_e32 v40, v56, v44
	s_waitcnt vmcnt(0)
	v_lshlrev_b32_e32 v62, 16, v42
	v_and_b32_e32 v63, 0xffff0000, v42
	v_lshlrev_b32_e32 v96, 16, v43
	v_and_b32_e32 v97, 0xffff0000, v43
	v_sub_f32_e32 v37, v36, v44
	v_sub_f32_e32 v36, v46, v44
	v_sub_f32_e32 v43, v55, v44
	v_sub_f32_e32 v42, v54, v44
	v_pk_mul_f32 v[38:39], v[44:45], v[38:39] op_sel:[1,0]
	v_pk_mul_f32 v[40:41], v[44:45], v[40:41] op_sel:[1,0]
	v_sub_f32_e32 v47, v61, v44
	v_sub_f32_e32 v46, v60, v44
	v_sub_f32_e32 v49, v59, v44
	v_sub_f32_e32 v48, v58, v44
	v_sub_f32_e32 v53, v63, v44
	v_sub_f32_e32 v52, v62, v44
	v_pk_mul_f32 v[36:37], v[44:45], v[36:37] op_sel:[1,0]
	v_pk_mul_f32 v[42:43], v[44:45], v[42:43] op_sel:[1,0]
	v_pk_fma_f32 v[38:39], v[78:79], v[38:39], v[66:67]
	v_pk_fma_f32 v[40:41], v[70:71], v[40:41], v[82:83]
	v_sub_f32_e32 v51, v97, v44
	v_sub_f32_e32 v50, v96, v44
	v_pk_mul_f32 v[48:49], v[44:45], v[48:49] op_sel:[1,0]
	v_pk_mul_f32 v[46:47], v[44:45], v[46:47] op_sel:[1,0]
	v_pk_mul_f32 v[52:53], v[44:45], v[52:53] op_sel:[1,0]
	v_pk_fma_f32 v[36:37], v[76:77], v[36:37], v[64:65]
	v_pk_fma_f32 v[42:43], v[68:69], v[42:43], v[80:81]
	v_pk_fma_f32 v[30:31], v[38:39], s[34:35], v[30:31] op_sel_hi:[1,0,1]
	v_cndmask_b32_e64 v39, v41, v57, s[10:11]
	v_cndmask_b32_e64 v38, v40, v56, s[10:11]
	v_pk_mul_f32 v[44:45], v[44:45], v[50:51] op_sel:[1,0]
	v_pk_fma_f32 v[46:47], v[74:75], v[46:47], v[86:87]
	v_pk_fma_f32 v[48:49], v[72:73], v[48:49], v[84:85]
	v_pk_fma_f32 v[50:51], v[88:89], v[52:53], v[92:93]
	v_pk_fma_f32 v[28:29], v[36:37], s[34:35], v[28:29] op_sel_hi:[1,0,1]
	v_cndmask_b32_e64 v37, v43, v55, s[10:11]
	v_cndmask_b32_e64 v36, v42, v54, s[10:11]
	v_pk_fma_f32 v[26:27], v[38:39], s[34:35], v[26:27] op_sel_hi:[1,0,1]
	v_cndmask_b32_e64 v40, v48, v58, s[10:11]
	v_cndmask_b32_e64 v42, v46, v60, s[10:11]
	v_cndmask_b32_e64 v46, v50, v62, s[10:11]
	v_cvt_pk_bf16_f32 v236, v28, v29
	v_add_f32_e32 v50, v28, v29
	v_mul_f32_e32 v55, v28, v28
	v_mul_f32_e32 v29, v29, v29
	v_pk_fma_f32 v[24:25], v[36:37], s[34:35], v[24:25] op_sel_hi:[1,0,1]
	v_mul_f32_e32 v28, v26, v26
	v_cndmask_b32_e64 v41, v49, v59, s[10:11]
	v_cvt_pk_bf16_f32 v237, v30, v31
	v_add_f32_e32 v52, v30, v31
	v_mul_f32_e32 v57, v30, v30
	v_mul_f32_e32 v31, v31, v31
	v_pk_fma_f32 v[58:59], v[26:27], v[26:27], v[28:29] op_sel_hi:[1,1,0]
	v_mov_b32_e32 v54, v24
	v_mov_b32_e32 v28, v25
	v_mov_b32_e32 v56, v26
	v_mov_b32_e32 v30, v27
	v_pk_fma_f32 v[44:45], v[90:91], v[44:45], v[94:95]
	v_cndmask_b32_e64 v43, v47, v61, s[10:11]
	v_cndmask_b32_e64 v47, v51, v63, s[10:11]
	v_cvt_pk_bf16_f32 v238, v24, v25
	v_mul_f32_e32 v51, v24, v24
	v_mul_f32_e32 v53, v25, v25
	v_pk_add_f32 v[24:25], v[54:55], v[28:29]
	v_pk_add_f32 v[28:29], v[56:57], v[30:31]
	v_pk_fma_f32 v[22:23], v[42:43], s[34:35], v[22:23] op_sel_hi:[1,0,1]
	v_pk_fma_f32 v[20:21], v[40:41], s[34:35], v[20:21] op_sel_hi:[1,0,1]
	v_cndmask_b32_e64 v45, v45, v97, s[10:11]
	v_cndmask_b32_e64 v44, v44, v96, s[10:11]
	v_pk_add_f32 v[24:25], v[24:25], v[28:29]
	v_pk_add_f32 v[28:29], v[50:51], v[52:53]
	v_mov_b32_e32 v165, v59
	v_mul_f32_e32 v39, v20, v20
	v_mul_f32_e32 v41, v21, v21
	v_mul_f32_e32 v43, v22, v22
	v_mul_f32_e32 v49, v23, v23
	v_pk_fma_f32 v[44:45], v[44:45], s[34:35], v[18:19] op_sel_hi:[1,0,1]
	v_pk_fma_f32 v[46:47], v[46:47], s[34:35], v[16:17] op_sel_hi:[1,0,1]
	v_pk_add_f32 v[28:29], v[28:29], v[164:165]
	v_mov_b32_e32 v38, v20
	v_mov_b32_e32 v40, v21
	v_mov_b32_e32 v42, v22
	v_mov_b32_e32 v48, v23
	v_mul_f32_e32 v17, v46, v46
	v_mul_f32_e32 v19, v47, v47
	v_mul_f32_e32 v61, v44, v44
	v_mul_f32_e32 v63, v45, v45
	v_pk_add_f32 v[24:25], v[24:25], v[28:29]
	v_pk_add_f32 v[28:29], v[38:39], v[40:41]
	v_pk_add_f32 v[30:31], v[42:43], v[48:49]
	v_mov_b32_e32 v16, v46
	v_mov_b32_e32 v18, v47
	v_mov_b32_e32 v60, v44
	v_mov_b32_e32 v62, v45
	v_pk_add_f32 v[28:29], v[28:29], v[30:31]
	v_pk_add_f32 v[16:17], v[16:17], v[18:19]
	v_pk_add_f32 v[18:19], v[60:61], v[62:63]
	v_pk_add_f32 v[24:25], v[24:25], v[28:29]
	v_pk_add_f32 v[16:17], v[16:17], v[18:19]
	v_cvt_pk_bf16_f32 v240, v20, v21
	v_pk_add_f32 v[16:17], v[24:25], v[16:17]
	ds_bpermute_b32 v18, v148, v16
	ds_bpermute_b32 v19, v148, v17
	v_cvt_pk_bf16_f32 v241, v22, v23
	v_cvt_pk_bf16_f32 v239, v26, v27
	v_cvt_pk_bf16_f32 v242, v46, v47
	s_waitcnt lgkmcnt(0)
	v_pk_add_f32 v[16:17], v[16:17], v[18:19]
	ds_bpermute_b32 v18, v149, v16
	ds_bpermute_b32 v19, v149, v17
	v_cvt_pk_bf16_f32 v243, v44, v45
	s_nop 1
	v_permlane16_swap_b32_e32 v236, v238
	v_permlane16_swap_b32_e32 v237, v239
	v_lshl_add_u64 v[244:245], v[34:35], 0, v[246:247]
	global_store_dwordx4 v[244:245], v[236:239], off
	s_nop 1
	v_permlane16_swap_b32_e32 v240, v242
	v_permlane16_swap_b32_e32 v241, v243
	global_store_dwordx4 v[244:245], v[240:243], off offset:256
	s_and_saveexec_b64 s[50:51], s[8:9]
	s_cbranch_execz .LBB0_1058
	s_waitcnt lgkmcnt(0)
	v_pk_add_f32 v[16:17], v[16:17], v[18:19]
	v_and_b32_e32 v18, 0xff, v32
	v_bfe_u32 v19, v208, 6, 2
	v_lshlrev_b32_e32 v18, 5, v18
	v_lshl_add_u32 v18, v19, 3, v18
	v_add_u32_e32 v18, 0x20800, v18
	ds_write_b64 v18, v[16:17]
; #define GASP __attribute__((address_space(1)))
;     __device__ __forceinline__ void operator()(Acc& acc, const Unit& u, int wr, int wc, int fr, int fq, LAS unsigned char* lds) const {
;     ...
;                 const int rl = ai * HALF + wr * 64 + m * 16 + fr, row = u.pm * BM + rl;
;                 const float* rp = (row < split) ? res0 + (size_t)row * D : res1 + (size_t)(row - split) * D;
;                 float* op = out + (size_t)row * D;
;                 f32x2 st = (f32x2){0.f, 1.f}; if (STp) st = SL[rl];
;                 float s = 0.f, q = 0.f;
; #pragma unroll
;                 for (int bj = 0; bj < 2; ++bj)
; #pragma unroll
;                     for (int n = 0; n < 2; ++n) { const int c = col0 + bj * HALF + n * 16; f32x4 r;
;                         if (resb) { const u32x2 w = *(const GASP u32x2*)(resb + (size_t)row * D + c);
;                             r = (f32x4){__uint_as_float(w.x << 16), __uint_as_float(w.x & 0xffff0000u), __uint_as_float(w.y << 16), __uint_as_float(w.y & 0xffff0000u)}; }
;                         else r = *(const GASP f32x4*)(rp + c);
;                         if (STp) r = (r - st[0]) * st[1] * gg[bj][n] + bb[bj][n];
;                         const f32x4 o = r * ALPHA + acc[ai][bj][m][n] * scale;
;                         if (out) *(GASP f32x4*)(op + c) = o;
;                         if (ob) { u32x2 w; w.x = pk2(o[0], o[1]); w.y = pk2(o[2], o[3]); *(GASP u32x2*)(ob + (size_t)row * D + c) = w; }
;                         s += (o[0] + o[1]) + (o[2] + o[3]); q += (o[0] * o[0] + o[1] * o[1]) + (o[2] * o[2] + o[3] * o[3]); }
;                 if (STn) { s += __shfl_xor(s, 16); s += __shfl_xor(s, 32); q += __shfl_xor(q, 16); q += __shfl_xor(q, 32);
;                     if (fq == 0) *(GASP f32x2*)(STn + (size_t)row * 32 + (u.pn * 4 + wc) * 2) = (f32x2){s, q}; }
.LBB0_1058:
	s_or_b64 exec, exec, s[50:51]
	v_add_u32_e32 v16, s37, v197
	v_ashrrev_i32_e32 v17, 31, v16
	v_cmp_gt_i32_e32 vcc, s73, v16
	s_nop 1
	v_cndmask_b32_e32 v17, 0, v17, vcc
	s_waitcnt lgkmcnt(0)
	v_lshlrev_b64 v[18:19], 11, v[16:17]
	v_lshl_add_u64 v[18:19], s[42:43], 0, v[18:19]
	v_lshl_add_u64 v[18:19], v[174:175], 1, v[18:19]
	global_load_dwordx2 v[20:21], v[18:19], off
	global_load_dwordx2 v[22:23], v[18:19], off offset:32
	global_load_dwordx2 v[24:25], v[18:19], off offset:256
	global_load_dwordx2 v[26:27], v[18:19], off offset:288
	ds_read_b64 v[28:29], v198
	s_waitcnt vmcnt(3)
	v_lshlrev_b32_e32 v31, 16, v21
	v_and_b32_e32 v32, 0xffff0000, v21
	s_waitcnt vmcnt(2)
	v_lshlrev_b32_e32 v40, 16, v23
	v_and_b32_e32 v41, 0xffff0000, v23
	v_lshlrev_b32_e32 v30, 16, v20
	v_and_b32_e32 v20, 0xffff0000, v20
	v_lshlrev_b32_e32 v38, 16, v22
	v_and_b32_e32 v39, 0xffff0000, v22
	s_waitcnt vmcnt(1)
	v_lshlrev_b32_e32 v42, 16, v24
	v_and_b32_e32 v43, 0xffff0000, v24
	v_lshlrev_b32_e32 v44, 16, v25
	v_and_b32_e32 v45, 0xffff0000, v25
	s_waitcnt lgkmcnt(0)
	v_sub_f32_e32 v23, v32, v28
	v_sub_f32_e32 v22, v31, v28
	v_sub_f32_e32 v25, v41, v28
	v_sub_f32_e32 v24, v40, v28
	s_waitcnt vmcnt(0)
	v_lshlrev_b32_e32 v46, 16, v26
	v_and_b32_e32 v47, 0xffff0000, v26
	v_lshlrev_b32_e32 v48, 16, v27
	v_and_b32_e32 v49, 0xffff0000, v27
	v_sub_f32_e32 v21, v20, v28
	v_sub_f32_e32 v20, v30, v28
	v_sub_f32_e32 v27, v39, v28
	v_sub_f32_e32 v26, v38, v28
	v_pk_mul_f32 v[22:23], v[28:29], v[22:23] op_sel:[1,0]
	v_pk_mul_f32 v[24:25], v[28:29], v[24:25] op_sel:[1,0]
	v_sub_f32_e32 v31, v45, v28
	v_sub_f32_e32 v30, v44, v28
	v_sub_f32_e32 v33, v43, v28
	v_sub_f32_e32 v32, v42, v28
	v_sub_f32_e32 v37, v47, v28
	v_sub_f32_e32 v36, v46, v28
	v_pk_mul_f32 v[20:21], v[28:29], v[20:21] op_sel:[1,0]
	v_pk_mul_f32 v[26:27], v[28:29], v[26:27] op_sel:[1,0]
	v_pk_fma_f32 v[22:23], v[78:79], v[22:23], v[66:67]
	v_pk_fma_f32 v[24:25], v[70:71], v[24:25], v[82:83]
	v_sub_f32_e32 v35, v49, v28
	v_sub_f32_e32 v34, v48, v28
	v_pk_mul_f32 v[32:33], v[28:29], v[32:33] op_sel:[1,0]
	v_pk_mul_f32 v[30:31], v[28:29], v[30:31] op_sel:[1,0]
	v_pk_mul_f32 v[36:37], v[28:29], v[36:37] op_sel:[1,0]
	v_pk_fma_f32 v[20:21], v[76:77], v[20:21], v[64:65]
	v_pk_fma_f32 v[26:27], v[68:69], v[26:27], v[80:81]
	v_pk_fma_f32 v[14:15], v[22:23], s[34:35], v[14:15] op_sel_hi:[1,0,1]
	v_cndmask_b32_e64 v23, v25, v41, s[10:11]
	v_cndmask_b32_e64 v22, v24, v40, s[10:11]
	v_pk_mul_f32 v[28:29], v[28:29], v[34:35] op_sel:[1,0]
	v_pk_fma_f32 v[30:31], v[74:75], v[30:31], v[86:87]
	v_pk_fma_f32 v[32:33], v[72:73], v[32:33], v[84:85]
	v_pk_fma_f32 v[34:35], v[88:89], v[36:37], v[92:93]
	v_pk_fma_f32 v[12:13], v[20:21], s[34:35], v[12:13] op_sel_hi:[1,0,1]
	v_cndmask_b32_e64 v21, v27, v39, s[10:11]
	v_cndmask_b32_e64 v20, v26, v38, s[10:11]
	v_pk_fma_f32 v[10:11], v[22:23], s[34:35], v[10:11] op_sel_hi:[1,0,1]
	v_cndmask_b32_e64 v24, v32, v42, s[10:11]
	v_cndmask_b32_e64 v26, v30, v44, s[10:11]
	v_cndmask_b32_e64 v30, v34, v46, s[10:11]
	v_cvt_pk_bf16_f32 v236, v12, v13
	v_add_f32_e32 v34, v12, v13
	v_mul_f32_e32 v39, v12, v12
	v_mul_f32_e32 v13, v13, v13
	v_pk_fma_f32 v[8:9], v[20:21], s[34:35], v[8:9] op_sel_hi:[1,0,1]
	v_mul_f32_e32 v12, v10, v10
	v_cndmask_b32_e64 v25, v33, v43, s[10:11]
	v_cvt_pk_bf16_f32 v237, v14, v15
	v_add_f32_e32 v36, v14, v15
	v_mul_f32_e32 v41, v14, v14
	v_mul_f32_e32 v15, v15, v15
	v_pk_fma_f32 v[42:43], v[10:11], v[10:11], v[12:13] op_sel_hi:[1,1,0]
	v_mov_b32_e32 v38, v8
	v_mov_b32_e32 v12, v9
	v_mov_b32_e32 v40, v10
	v_mov_b32_e32 v14, v11
	v_pk_fma_f32 v[28:29], v[90:91], v[28:29], v[94:95]
	v_cndmask_b32_e64 v27, v31, v45, s[10:11]
	v_cndmask_b32_e64 v31, v35, v47, s[10:11]
	v_cvt_pk_bf16_f32 v238, v8, v9
	v_mul_f32_e32 v35, v8, v8
	v_mul_f32_e32 v37, v9, v9
	v_pk_add_f32 v[8:9], v[38:39], v[12:13]
	v_pk_add_f32 v[12:13], v[40:41], v[14:15]
	v_pk_fma_f32 v[6:7], v[26:27], s[34:35], v[6:7] op_sel_hi:[1,0,1]
	v_pk_fma_f32 v[4:5], v[24:25], s[34:35], v[4:5] op_sel_hi:[1,0,1]
	v_cndmask_b32_e64 v29, v29, v49, s[10:11]
	v_cndmask_b32_e64 v28, v28, v48, s[10:11]
	v_pk_add_f32 v[8:9], v[8:9], v[12:13]
	v_pk_add_f32 v[12:13], v[34:35], v[36:37]
	v_mov_b32_e32 v165, v43
	v_mul_f32_e32 v23, v4, v4
	v_mul_f32_e32 v25, v5, v5
	v_mul_f32_e32 v27, v6, v6
	v_mul_f32_e32 v33, v7, v7
	v_pk_fma_f32 v[28:29], v[28:29], s[34:35], v[2:3] op_sel_hi:[1,0,1]
	v_pk_fma_f32 v[30:31], v[30:31], s[34:35], v[0:1] op_sel_hi:[1,0,1]
	v_pk_add_f32 v[12:13], v[12:13], v[164:165]
	v_mov_b32_e32 v22, v4
	v_mov_b32_e32 v24, v5
	v_mov_b32_e32 v26, v6
	v_mov_b32_e32 v32, v7
	v_mul_f32_e32 v1, v30, v30
	v_mul_f32_e32 v3, v31, v31
	v_mul_f32_e32 v45, v28, v28
	v_mul_f32_e32 v47, v29, v29
	v_pk_add_f32 v[8:9], v[8:9], v[12:13]
	v_pk_add_f32 v[12:13], v[22:23], v[24:25]
	v_pk_add_f32 v[14:15], v[26:27], v[32:33]
	v_mov_b32_e32 v0, v30
	v_mov_b32_e32 v2, v31
	v_mov_b32_e32 v44, v28
	v_mov_b32_e32 v46, v29
	v_pk_add_f32 v[12:13], v[12:13], v[14:15]
	v_pk_add_f32 v[0:1], v[0:1], v[2:3]
	v_pk_add_f32 v[2:3], v[44:45], v[46:47]
	v_pk_add_f32 v[8:9], v[8:9], v[12:13]
	v_pk_add_f32 v[0:1], v[0:1], v[2:3]
	v_cvt_pk_bf16_f32 v240, v4, v5
	v_pk_add_f32 v[0:1], v[8:9], v[0:1]
	ds_bpermute_b32 v2, v148, v0
	ds_bpermute_b32 v3, v148, v1
	v_cvt_pk_bf16_f32 v241, v6, v7
	v_cvt_pk_bf16_f32 v239, v10, v11
	v_cvt_pk_bf16_f32 v242, v30, v31
	s_waitcnt lgkmcnt(0)
	v_pk_add_f32 v[0:1], v[0:1], v[2:3]
	ds_bpermute_b32 v2, v149, v0
	ds_bpermute_b32 v3, v149, v1
	v_cvt_pk_bf16_f32 v243, v28, v29
	s_nop 1
	v_permlane16_swap_b32_e32 v236, v238
	v_permlane16_swap_b32_e32 v237, v239
	v_lshl_add_u64 v[244:245], v[18:19], 0, v[246:247]
	global_store_dwordx4 v[244:245], v[236:239], off
	s_nop 1
	v_permlane16_swap_b32_e32 v240, v242
	v_permlane16_swap_b32_e32 v241, v243
	global_store_dwordx4 v[244:245], v[240:243], off offset:256
	s_and_saveexec_b64 s[50:51], s[8:9]
	s_cbranch_execz .LBB0_1060
	s_waitcnt lgkmcnt(0)
	v_pk_add_f32 v[0:1], v[0:1], v[2:3]
	v_and_b32_e32 v2, 0xff, v16
	v_bfe_u32 v3, v208, 6, 2
	v_lshlrev_b32_e32 v2, 5, v2
	v_lshl_add_u32 v2, v3, 3, v2
	v_add_u32_e32 v2, 0x20800, v2
	ds_write_b64 v2, v[0:1]
.LBB0_1060:
	s_or_b64 exec, exec, s[50:51]
	s_waitcnt lgkmcnt(0)
	s_barrier
	v_lshlrev_b32_e32 v236, 4, v208
	v_add_u32_e32 v236, 0x20800, v236
	ds_read_b128 v[240:243], v236
	v_readfirstlane_b32 s98, v16
	s_andn2_b32 s98, s98, 0xff
	v_lshrrev_b32_e32 v237, 1, v208
	v_add_u32_e32 v237, s98, v237
	v_lshlrev_b32_e32 v237, 7, v237
	v_and_b32_e32 v238, 1, v208
	v_lshl_add_u32 v237, v238, 4, v237
	s_lshl_b32 s99, s14, 2
	s_and_b32 s99, s99, 0xffffffe0
	v_add_u32_e32 v237, s99, v237
	s_waitcnt lgkmcnt(0)
	global_store_dwordx4 v237, v[240:243], s[24:25]
	s_andn2_b64 vcc, exec, s[12:13]
	s_mov_b64 s[12:13], -1
	s_cbranch_vccnz .LBB0_1031
	s_andn2_b64 vcc, exec, s[20:21]
	s_cbranch_vccnz .LBB0_1030
	s_barrier
	s_branch .LBB0_1030
